# gdn_prep step 1: seven of the nine second-half row loads issued ~780 instructions earlier into registers free during the first half
# speedup vs baseline: 1.0051x; 1.0051x over previous
.LBB0_283:
	s_mov_b32 s40, 0
	s_ashr_i32 s41, s40, 31
	s_andn2_b64 vcc, exec, s[30:31]
	s_mov_b64 s[28:29], -1
	v_readlane_b32 s100, v255, 42
	s_nop 3
	s_cmp_lg_u32 s100, 0
	s_cbranch_scc1 .LBB0_282
	s_cbranch_vccnz .LBB0_287
	s_lshl_b64 s[28:29], s[40:41], 2
	s_add_u32 s28, s46, s28
	s_addc_u32 s29, s47, s29
	v_lshl_add_u64 v[0:1], v[48:49], 0, s[28:29]
	v_add_co_u32_e32 v4, vcc, 0x3000, v0
	s_mov_b64 s[8:9], 0x3000
	s_nop 0
	v_addc_co_u32_e32 v5, vcc, 0, v1, vcc
	global_load_dwordx4 v[24:27], v[0:1], off offset:16
	global_load_dwordx4 v[28:31], v[0:1], off
	v_lshl_add_u64 v[2:3], v[0:1], 0, s[8:9]
	global_load_dwordx4 v[12:15], v[4:5], off
	global_load_dwordx4 v[8:11], v[2:3], off offset:16
	s_mov_b64 s[28:29], 0x6000
	v_add_co_u32_e32 v4, vcc, s83, v0
	v_lshl_add_u64 v[2:3], v[0:1], 0, s[28:29]
	s_nop 0
	v_addc_co_u32_e32 v5, vcc, 0, v1, vcc
	s_mov_b64 s[28:29], 0x9000
	global_load_dwordx4 v[20:23], v[4:5], off
	global_load_dwordx4 v[16:19], v[2:3], off offset:16
	v_lshl_add_u64 v[2:3], v[0:1], 0, s[28:29]
	s_lshl_b64 s[28:29], s[40:41], 1
	s_add_u32 s28, s74, s28
	v_add_co_u32_e32 v0, vcc, 0x9000, v0
	s_addc_u32 s29, s75, s29
	s_nop 0
	v_addc_co_u32_e32 v1, vcc, 0, v1, vcc
	v_lshl_add_u64 v[66:67], s[28:29], 0, v[50:51]
	global_load_dwordx4 v[4:7], v[0:1], off
	s_nop 0
	global_load_dwordx4 v[0:3], v[2:3], off offset:16
	v_add_co_u32_e32 v62, vcc, 0x13095000, v66
	s_nop 1
	v_addc_co_u32_e32 v63, vcc, 0, v67, vcc
	global_load_dwordx4 v[112:115], v[62:63], off offset:2560
	v_add_co_u32_e32 v62, vcc, 0x13099000, v66
	s_nop 1
	v_addc_co_u32_e32 v63, vcc, 0, v67, vcc
	global_load_dwordx4 v[116:119], v[62:63], off offset:3072
	v_add_co_u32_e32 v62, vcc, 0x1309d000, v66
	s_nop 1
	v_addc_co_u32_e32 v63, vcc, 0, v67, vcc
	global_load_dwordx4 v[222:225], v[62:63], off offset:3584
	v_add_co_u32_e32 v62, vcc, 0x130a2000, v66
	s_nop 1
	v_addc_co_u32_e32 v63, vcc, 0, v67, vcc
	global_load_dwordx4 v[226:229], v[62:63], off
	v_add_co_u32_e32 v62, vcc, 0x130a6000, v66
	s_nop 1
	v_addc_co_u32_e32 v63, vcc, 0, v67, vcc
	global_load_dwordx4 v[230:233], v[62:63], off offset:512
	v_add_co_u32_e32 v62, vcc, 0x130aa000, v66
	s_nop 1
	v_addc_co_u32_e32 v63, vcc, 0, v67, vcc
	global_load_dwordx4 v[234:237], v[62:63], off offset:1024
	v_add_co_u32_e32 v62, vcc, 0x130ae000, v66
	s_nop 1
	v_addc_co_u32_e32 v63, vcc, 0, v67, vcc
	global_load_dwordx4 v[242:245], v[62:63], off offset:1536
	v_add_co_u32_e32 v62, vcc, 0x130b2000, v66
	s_nop 1
	v_addc_co_u32_e32 v63, vcc, 0, v67, vcc
	global_load_dwordx4 v[246:249], v[62:63], off offset:2048
	v_add_co_u32_e32 v62, vcc, 0x130b6000, v66
	s_nop 1
	v_addc_co_u32_e32 v63, vcc, 0, v67, vcc
	global_load_dwordx2 v[80:81], v[62:63], off offset:2560
	global_load_dwordx2 v[86:87], v[62:63], off offset:2568
	v_add_co_u32_e32 v62, vcc, 0x130ba000, v66
	s_nop 1
	v_addc_co_u32_e32 v63, vcc, 0, v67, vcc
	global_load_dwordx4 v[62:65], v[62:63], off offset:3072
	s_waitcnt vmcnt(10)
	v_cndmask_b32_e64 v76, v112, 0, s[56:57]
	v_cndmask_b32_e64 v75, v113, 0, s[56:57]
	v_cndmask_b32_e64 v68, v115, 0, s[56:57]
	v_cndmask_b32_e64 v69, v114, 0, s[56:57]
	v_lshlrev_b32_e32 v70, 16, v76
	v_lshlrev_b32_e32 v102, 16, v69
	v_and_b32_e32 v106, 0xffff0000, v69
	v_lshlrev_b32_e32 v152, 16, v68
	v_and_b32_e32 v220, 0xffff0000, v68
	v_and_b32_e32 v76, 0xffff0000, v76
	v_lshlrev_b32_e32 v84, 16, v75
	v_and_b32_e32 v98, 0xffff0000, v75
	s_waitcnt vmcnt(9)
	v_cndmask_b32_e64 v77, v116, 0, s[58:59]
	v_cndmask_b32_e64 v94, v117, 0, s[58:59]
	v_cndmask_b32_e64 v92, v119, 0, s[58:59]
	v_cndmask_b32_e64 v93, v118, 0, s[58:59]
	v_lshlrev_b32_e32 v71, 16, v77
	v_and_b32_e32 v77, 0xffff0000, v77
	v_lshlrev_b32_e32 v85, 16, v94
	v_and_b32_e32 v99, 0xffff0000, v94
	v_lshlrev_b32_e32 v103, 16, v93
	v_and_b32_e32 v107, 0xffff0000, v93
	v_lshlrev_b32_e32 v153, 16, v92
	v_and_b32_e32 v221, 0xffff0000, v92
	s_waitcnt vmcnt(8)
	v_cndmask_b32_e64 v95, v222, 0, s[60:61]
	v_cndmask_b32_e64 v74, v223, 0, s[60:61]
	v_cndmask_b32_e64 v82, v225, 0, s[60:61]
	v_cndmask_b32_e64 v78, v224, 0, s[60:61]
	v_lshlrev_b32_e32 v68, 16, v95
	s_waitcnt vmcnt(7)
	v_cndmask_b32_e64 v96, v226, 0, s[48:49]
	v_cndmask_b32_e64 v110, v227, 0, s[48:49]
	v_cndmask_b32_e64 v83, v229, 0, s[48:49]
	v_cndmask_b32_e64 v79, v228, 0, s[48:49]
	v_lshlrev_b32_e32 v69, 16, v96
	v_and_b32_e32 v75, 0xffff0000, v110
	s_waitcnt vmcnt(6)
	v_cndmask_b32_e64 v135, v230, 0, s[48:49]
	v_cndmask_b32_e64 v132, v231, 0, s[48:49]
	v_cndmask_b32_e64 v126, v233, 0, s[48:49]
	v_cndmask_b32_e64 v122, v232, 0, s[48:49]
	s_waitcnt vmcnt(5)
	v_cndmask_b32_e64 v136, v234, 0, s[48:49]
	v_cndmask_b32_e64 v133, v235, 0, s[48:49]
	v_cndmask_b32_e64 v127, v237, 0, s[48:49]
	v_cndmask_b32_e64 v123, v236, 0, s[48:49]
	s_waitcnt vmcnt(4)
	v_cndmask_b32_e64 v128, v242, 0, s[48:49]
	v_cndmask_b32_e64 v130, v243, 0, s[48:49]
	v_cndmask_b32_e64 v191, v245, 0, s[48:49]
	v_cndmask_b32_e64 v124, v244, 0, s[48:49]
	s_waitcnt vmcnt(3)
	v_cndmask_b32_e64 v129, v246, 0, s[48:49]
	v_cndmask_b32_e64 v131, v247, 0, s[48:49]
	v_cndmask_b32_e64 v216, v249, 0, s[48:49]
	v_cndmask_b32_e64 v125, v248, 0, s[48:49]
	s_waitcnt vmcnt(1)
	v_cndmask_b32_e64 v192, v80, 0, s[48:49]
	v_cndmask_b32_e64 v212, v81, 0, s[48:49]
	v_cndmask_b32_e64 v193, v87, 0, s[48:49]
	v_cndmask_b32_e64 v194, v86, 0, s[48:49]
	s_waitcnt vmcnt(0)
	v_cndmask_b32_e64 v195, v65, 0, s[48:49]
	v_cndmask_b32_e64 v213, v64, 0, s[48:49]
	v_cndmask_b32_e64 v214, v63, 0, s[48:49]
	v_cndmask_b32_e64 v215, v62, 0, s[48:49]
	v_mov_b32_e32 v64, v28
	v_mov_b32_e32 v65, v12
	v_mov_b32_e32 v62, v30
	v_mov_b32_e32 v63, v14
	v_mov_b32_e32 v14, v31
	v_mov_b32_e32 v30, v24
	v_mov_b32_e32 v31, v8
	v_mov_b32_e32 v8, v25
	v_pk_mov_b32 v[24:25], v[70:71], v[68:69] op_sel:[1,0]
	v_pk_mul_f32 v[72:73], v[64:65], v[70:71]
	v_pk_mul_f32 v[116:117], v[64:65], v[24:25]
	v_mov_b32_e32 v24, v20
	v_mov_b32_e32 v25, v4
	v_mov_b32_e32 v12, v29
	v_mov_b32_e32 v28, v26
	v_mov_b32_e32 v29, v10
	v_mov_b32_e32 v10, v27
	v_pk_mul_f32 v[26:27], v[24:25], v[68:69]
	v_add_f32_e32 v4, v72, v73
	v_add_f32_e32 v4, v4, v26
	v_and_b32_e32 v71, 0xffff0000, v96
	v_and_b32_e32 v70, 0xffff0000, v95
	v_pk_mul_f32 v[80:81], v[12:13], v[76:77]
	v_add_f32_e32 v134, v4, v27
	v_pk_mov_b32 v[26:27], v[76:77], v[70:71] op_sel:[1,0]
	v_mov_b32_e32 v4, v21
	v_pk_mul_f32 v[94:95], v[12:13], v[26:27]
	v_pk_mul_f32 v[20:21], v[4:5], v[70:71]
	v_add_f32_e32 v26, v80, v81
	v_add_f32_e32 v20, v26, v20
	v_lshlrev_b32_e32 v73, 16, v110
	v_lshlrev_b32_e32 v72, 16, v74
	v_add_f32_e32 v137, v20, v21
	v_pk_mov_b32 v[20:21], v[84:85], v[72:73] op_sel:[1,0]
	v_pk_mul_f32 v[86:87], v[62:63], v[84:85]
	v_pk_mul_f32 v[118:119], v[62:63], v[20:21]
	v_mov_b32_e32 v20, v22
	v_mov_b32_e32 v21, v6
	v_pk_mul_f32 v[26:27], v[20:21], v[72:73]
	v_add_f32_e32 v6, v86, v87
	v_add_f32_e32 v6, v6, v26
	v_and_b32_e32 v74, 0xffff0000, v74
	v_pk_mul_f32 v[100:101], v[14:15], v[98:99]
	v_add_f32_e32 v86, v6, v27
	v_pk_mov_b32 v[26:27], v[98:99], v[74:75] op_sel:[1,0]
	v_mov_b32_e32 v6, v23
	v_pk_mul_f32 v[98:99], v[14:15], v[26:27]
	v_pk_mul_f32 v[22:23], v[6:7], v[74:75]
	v_add_f32_e32 v26, v100, v101
	v_add_f32_e32 v22, v26, v22
	v_lshlrev_b32_e32 v77, 16, v79
	v_lshlrev_b32_e32 v76, 16, v78
	v_add_f32_e32 v87, v22, v23
	v_pk_mov_b32 v[22:23], v[102:103], v[76:77] op_sel:[1,0]
	v_pk_mul_f32 v[104:105], v[30:31], v[102:103]
	v_pk_mul_f32 v[120:121], v[30:31], v[22:23]
	v_mov_b32_e32 v22, v16
	v_mov_b32_e32 v23, v0
	v_pk_mul_f32 v[26:27], v[22:23], v[76:77]
	v_add_f32_e32 v0, v104, v105
	v_add_f32_e32 v0, v0, v26
	v_and_b32_e32 v79, 0xffff0000, v79
	v_and_b32_e32 v78, 0xffff0000, v78
	v_pk_mul_f32 v[112:113], v[8:9], v[106:107]
	v_pk_mul_f32 v[218:219], v[28:29], v[152:153]
	v_add_f32_e32 v152, v0, v27
	v_pk_mov_b32 v[26:27], v[106:107], v[78:79] op_sel:[1,0]
	v_mov_b32_e32 v0, v17
	v_pk_mul_f32 v[102:103], v[8:9], v[26:27]
	v_pk_mul_f32 v[16:17], v[0:1], v[78:79]
	v_add_f32_e32 v26, v112, v113
	v_add_f32_e32 v16, v26, v16
	v_lshlrev_b32_e32 v81, 16, v83
	v_lshlrev_b32_e32 v80, 16, v82
	v_add_f32_e32 v217, v16, v17
	v_pk_mov_b32 v[16:17], v[152:153], v[80:81] op_sel:[1,0]
	v_mov_b32_e32 v26, v18
	v_mov_b32_e32 v27, v2
	v_pk_mul_f32 v[112:113], v[28:29], v[16:17]
	v_pk_mul_f32 v[16:17], v[26:27], v[80:81]
	v_add_f32_e32 v2, v218, v219
	v_add_f32_e32 v2, v2, v16
	v_and_b32_e32 v83, 0xffff0000, v83
	v_and_b32_e32 v82, 0xffff0000, v82
	v_pk_mul_f32 v[222:223], v[10:11], v[220:221]
	v_add_f32_e32 v18, v2, v17
	v_pk_mov_b32 v[16:17], v[220:221], v[82:83] op_sel:[1,0]
	v_mov_b32_e32 v2, v19
	v_pk_mul_f32 v[84:85], v[10:11], v[16:17]
	v_pk_mul_f32 v[16:17], v[2:3], v[82:83]
	v_add_f32_e32 v19, v222, v223
	s_mov_b32 s101, 0
	s_mov_b32 s100, 0x130c3000
	v_lshl_add_u64 v[220:221], v[66:67], 0, s[100:101]
	global_load_dwordx4 v[220:223], v[220:221], off
	s_mov_b32 s100, 0x130be000
	v_lshl_add_u64 v[224:225], v[66:67], 0, s[100:101]
	global_load_dwordx4 v[224:227], v[224:225], off offset:3584
	s_mov_b32 s100, 0x130df000
	v_lshl_add_u64 v[228:229], v[66:67], 0, s[100:101]
	global_load_dwordx4 v[228:231], v[228:229], off offset:3584
	s_mov_b32 s100, 0x130cf000
	v_lshl_add_u64 v[232:233], v[66:67], 0, s[100:101]
	global_load_dwordx4 v[232:235], v[232:233], off offset:1536
	s_mov_b32 s100, 0x130d3000
	v_lshl_add_u64 v[236:237], v[66:67], 0, s[100:101]
	global_load_dwordx4 v[236:239], v[236:237], off offset:2048
	s_mov_b32 s100, 0x130c7000
	v_lshl_add_u64 v[242:243], v[66:67], 0, s[100:101]
	global_load_dwordx4 v[242:245], v[242:243], off offset:512
	s_mov_b32 s100, 0x130cb000
	v_lshl_add_u64 v[246:247], v[66:67], 0, s[100:101]
	global_load_dwordx4 v[246:249], v[246:247], off offset:1024
	v_add_f32_e32 v16, v19, v16
	v_mul_f32_e32 v19, 0xbfb8aa3b, v137
	v_exp_f32_e32 v19, v19
	v_mul_f32_e32 v153, 0xbfb8aa3b, v18
	v_exp_f32_e32 v153, v153
	v_add_f32_e32 v16, v16, v17
	v_add_f32_e32 v19, 1.0, v19
	v_rcp_f32_e32 v19, v19
	v_add_f32_e32 v153, 1.0, v153
	v_rcp_f32_e32 v153, v153
	v_mul_f32_e32 v17, 0xbfb8aa3b, v134
	v_mul_f32_e32 v19, v137, v19
	v_mul_f32_e32 v137, 0xbfb8aa3b, v86
	v_exp_f32_e32 v137, v137
	v_exp_f32_e32 v17, v17
	v_mul_f32_e32 v153, v18, v153
	v_mul_f32_e32 v18, 0xbfb8aa3b, v16
	v_add_f32_e32 v137, 1.0, v137
	v_rcp_f32_e32 v137, v137
	v_exp_f32_e32 v18, v18
	v_add_f32_e32 v17, 1.0, v17
	v_rcp_f32_e32 v17, v17
	v_mul_f32_e32 v86, v86, v137
	v_mul_f32_e32 v137, 0xbfb8aa3b, v87
	v_exp_f32_e32 v137, v137
	v_add_f32_e32 v18, 1.0, v18
	v_rcp_f32_e32 v18, v18
	v_mul_f32_e32 v17, v134, v17
	v_add_f32_e32 v137, 1.0, v137
	v_rcp_f32_e32 v137, v137
	v_mul_f32_e32 v134, v19, v19
	v_fmac_f32_e32 v134, v17, v17
	v_fmac_f32_e32 v134, v86, v86
	v_mul_f32_e32 v87, v87, v137
	v_mul_f32_e32 v137, 0xbfb8aa3b, v152
	v_exp_f32_e32 v137, v137
	v_fmac_f32_e32 v134, v87, v87
	v_pk_mul_f32 v[92:93], v[64:65], v[68:69]
	v_add_f32_e32 v116, v116, v117
	v_add_f32_e32 v137, 1.0, v137
	v_rcp_f32_e32 v137, v137
	v_pk_mul_f32 v[108:109], v[12:13], v[70:71]
	v_add_f32_e32 v94, v94, v95
	v_pk_mul_f32 v[96:97], v[62:63], v[72:73]
	v_mul_f32_e32 v137, v152, v137
	v_mul_f32_e32 v152, 0xbfb8aa3b, v217
	v_exp_f32_e32 v152, v152
	v_fmac_f32_e32 v134, v137, v137
	v_pk_mul_f32 v[114:115], v[14:15], v[74:75]
	v_add_f32_e32 v98, v98, v99
	v_add_f32_e32 v152, 1.0, v152
	v_rcp_f32_e32 v152, v152
	v_pk_mul_f32 v[100:101], v[30:31], v[76:77]
	v_add_f32_e32 v120, v120, v121
	v_pk_mul_f32 v[110:111], v[8:9], v[78:79]
	v_mul_f32_e32 v152, v217, v152
	v_mul_f32_e32 v217, v16, v18
	v_cvt_pk_bf16_f32 v16, v17, v19
	v_cvt_pk_bf16_f32 v17, v86, v87
	v_lshlrev_b32_e32 v87, 16, v136
	v_lshlrev_b32_e32 v86, 16, v135
	v_cvt_pk_bf16_f32 v18, v137, v152
	v_cvt_pk_bf16_f32 v19, v153, v217
	ds_write_b128 v169, v[16:19]
	v_pk_mov_b32 v[16:17], v[68:69], v[86:87] op_sel:[1,0]
	v_fmac_f32_e32 v134, v152, v152
	v_pk_mul_f32 v[68:69], v[64:65], v[16:17]
	v_pk_mul_f32 v[16:17], v[24:25], v[16:17]
	v_pk_mul_f32 v[18:19], v[24:25], v[86:87]
	v_add_f32_e32 v16, v116, v16
	v_add_f32_e32 v16, v16, v17
	v_mul_f32_e32 v17, 0xbfb8aa3b, v16
	v_exp_f32_e32 v17, v17
	v_fmac_f32_e32 v134, v153, v153
	v_fmac_f32_e32 v134, v217, v217
	v_add_f32_e32 v102, v102, v103
	v_add_f32_e32 v17, 1.0, v17
	v_rcp_f32_e32 v17, v17
	v_pk_mul_f32 v[104:105], v[28:29], v[80:81]
	v_pk_mul_f32 v[106:107], v[10:11], v[82:83]
	v_add_f32_e32 v104, v104, v105
	v_mul_f32_e32 v152, v16, v17
	v_add_f32_e32 v16, v92, v93
	v_add_f32_e32 v16, v16, v18
	v_and_b32_e32 v93, 0xffff0000, v136
	v_and_b32_e32 v92, 0xffff0000, v135
	v_add_f32_e32 v137, v16, v19
	v_pk_mov_b32 v[16:17], v[70:71], v[92:93] op_sel:[1,0]
	v_pk_mul_f32 v[18:19], v[4:5], v[92:93]
	v_pk_mul_f32 v[70:71], v[12:13], v[16:17]
	v_pk_mul_f32 v[16:17], v[4:5], v[16:17]
	v_and_b32_e32 v105, 0xffff0000, v127
	v_add_f32_e32 v16, v94, v16
	v_add_f32_e32 v16, v16, v17
	v_mul_f32_e32 v17, 0xbfb8aa3b, v16
	v_exp_f32_e32 v17, v17
	v_add_f32_e32 v84, v84, v85
	v_pk_mul_f32 v[116:117], v[64:65], v[86:87]
	v_add_f32_e32 v17, 1.0, v17
	v_rcp_f32_e32 v17, v17
	v_add_f32_e32 v68, v68, v69
	v_and_b32_e32 v69, 0xffff0000, v129
	v_pk_mul_f32 v[94:95], v[12:13], v[92:93]
	v_mul_f32_e32 v16, v16, v17
	v_add_f32_e32 v17, v108, v109
	v_add_f32_e32 v17, v17, v18
	v_lshlrev_b32_e32 v109, 16, v133
	v_lshlrev_b32_e32 v108, 16, v132
	v_add_f32_e32 v136, v17, v19
	v_pk_mov_b32 v[18:19], v[72:73], v[108:109] op_sel:[1,0]
	v_add_f32_e32 v17, v118, v119
	v_pk_mul_f32 v[72:73], v[62:63], v[18:19]
	v_pk_mul_f32 v[18:19], v[20:21], v[18:19]
	v_mul_f32_e32 v135, v16, v16
	v_add_f32_e32 v17, v17, v18
	v_add_f32_e32 v17, v17, v19
	v_mul_f32_e32 v18, 0xbfb8aa3b, v17
	v_exp_f32_e32 v18, v18
	v_fmac_f32_e32 v135, v152, v152
	v_cvt_pk_bf16_f32 v16, v152, v16
	v_pk_mul_f32 v[152:153], v[20:21], v[108:109]
	v_add_f32_e32 v18, 1.0, v18
	v_rcp_f32_e32 v18, v18
	v_add_f32_e32 v70, v70, v71
	v_pk_mul_f32 v[118:119], v[62:63], v[108:109]
	v_mul_f32_e32 v17, v17, v18
	v_add_f32_e32 v18, v96, v97
	v_add_f32_e32 v18, v18, v152
	v_and_b32_e32 v97, 0xffff0000, v133
	v_and_b32_e32 v96, 0xffff0000, v132
	v_add_f32_e32 v152, v18, v153
	v_pk_mov_b32 v[18:19], v[74:75], v[96:97] op_sel:[1,0]
	v_fmac_f32_e32 v135, v17, v17
	v_pk_mul_f32 v[74:75], v[14:15], v[18:19]
	v_pk_mul_f32 v[18:19], v[6:7], v[18:19]
	v_pk_mul_f32 v[132:133], v[6:7], v[96:97]
	v_add_f32_e32 v18, v98, v18
	v_add_f32_e32 v18, v18, v19
	v_mul_f32_e32 v19, 0xbfb8aa3b, v18
	v_exp_f32_e32 v19, v19
	v_pk_mul_f32 v[98:99], v[14:15], v[96:97]
	v_add_f32_e32 v74, v74, v75
	v_add_f32_e32 v19, 1.0, v19
	v_rcp_f32_e32 v19, v19
	s_nop 0
	v_mul_f32_e32 v18, v18, v19
	v_fmac_f32_e32 v135, v18, v18
	v_cvt_pk_bf16_f32 v17, v17, v18
	v_add_f32_e32 v18, v114, v115
	v_add_f32_e32 v18, v18, v132
	v_lshlrev_b32_e32 v115, 16, v123
	v_lshlrev_b32_e32 v114, 16, v122
	v_add_f32_e32 v153, v18, v133
	v_pk_mov_b32 v[18:19], v[76:77], v[114:115] op_sel:[1,0]
	v_pk_mul_f32 v[132:133], v[22:23], v[114:115]
	v_pk_mul_f32 v[76:77], v[30:31], v[18:19]
	v_pk_mul_f32 v[18:19], v[22:23], v[18:19]
	v_add_f32_e32 v76, v76, v77
	v_add_f32_e32 v18, v120, v18
	v_add_f32_e32 v18, v18, v19
	v_mul_f32_e32 v19, 0xbfb8aa3b, v18
	v_exp_f32_e32 v19, v19
	v_pk_mul_f32 v[120:121], v[30:31], v[114:115]
	v_and_b32_e32 v77, 0xffff0000, v125
	v_add_f32_e32 v19, 1.0, v19
	v_rcp_f32_e32 v19, v19
	s_nop 0
	v_mul_f32_e32 v217, v18, v19
	v_add_f32_e32 v18, v100, v101
	v_add_f32_e32 v18, v18, v132
	v_and_b32_e32 v101, 0xffff0000, v123
	v_and_b32_e32 v100, 0xffff0000, v122
	v_add_f32_e32 v218, v18, v133
	v_pk_mov_b32 v[18:19], v[78:79], v[100:101] op_sel:[1,0]
	v_pk_mul_f32 v[122:123], v[0:1], v[100:101]
	v_pk_mul_f32 v[78:79], v[8:9], v[18:19]
	v_pk_mul_f32 v[18:19], v[0:1], v[18:19]
	v_fmac_f32_e32 v135, v217, v217
	v_add_f32_e32 v18, v102, v18
	v_add_f32_e32 v18, v18, v19
	v_mul_f32_e32 v19, 0xbfb8aa3b, v18
	v_exp_f32_e32 v19, v19
	v_pk_mul_f32 v[102:103], v[8:9], v[100:101]
	v_add_f32_e32 v78, v78, v79
	v_add_f32_e32 v19, 1.0, v19
	v_rcp_f32_e32 v19, v19
	s_nop 0
	v_mul_f32_e32 v18, v18, v19
	v_add_f32_e32 v19, v110, v111
	v_add_f32_e32 v19, v19, v122
	v_lshlrev_b32_e32 v111, 16, v127
	v_lshlrev_b32_e32 v110, 16, v126
	v_fmac_f32_e32 v135, v18, v18
	v_cvt_pk_bf16_f32 v18, v217, v18
	v_add_f32_e32 v217, v19, v123
	v_pk_mov_b32 v[122:123], v[80:81], v[110:111] op_sel:[1,0]
	v_add_f32_e32 v19, v112, v113
	v_pk_mul_f32 v[80:81], v[28:29], v[122:123]
	v_pk_mul_f32 v[122:123], v[26:27], v[122:123]
	v_pk_mul_f32 v[132:133], v[26:27], v[110:111]
	v_add_f32_e32 v19, v19, v122
	v_add_f32_e32 v19, v19, v123
	v_mul_f32_e32 v112, 0xbfb8aa3b, v19
	v_exp_f32_e32 v112, v112
	v_add_f32_e32 v104, v104, v132
	v_add_f32_e32 v132, v104, v133
	v_and_b32_e32 v104, 0xffff0000, v126
	v_add_f32_e32 v112, 1.0, v112
	v_rcp_f32_e32 v112, v112
	v_pk_mul_f32 v[126:127], v[2:3], v[104:105]
	v_pk_mul_f32 v[122:123], v[28:29], v[110:111]
	v_mul_f32_e32 v19, v19, v112
	v_pk_mov_b32 v[112:113], v[82:83], v[104:105] op_sel:[1,0]
	v_fmac_f32_e32 v135, v19, v19
	v_pk_mul_f32 v[82:83], v[10:11], v[112:113]
	v_pk_mul_f32 v[112:113], v[2:3], v[112:113]
	v_add_f32_e32 v82, v82, v83
	v_add_f32_e32 v84, v84, v112
	v_add_f32_e32 v84, v84, v113
	v_mul_f32_e32 v85, 0xbfb8aa3b, v84
	v_exp_f32_e32 v85, v85
	v_mul_f32_e32 v113, 0xbfb8aa3b, v132
	v_exp_f32_e32 v113, v113
	v_add_f32_e32 v85, 1.0, v85
	v_rcp_f32_e32 v85, v85
	v_add_f32_e32 v113, 1.0, v113
	v_rcp_f32_e32 v113, v113
	v_mul_f32_e32 v112, v84, v85
	v_cvt_pk_bf16_f32 v19, v19, v112
	ds_write_b128 v169, v[16:19] offset:272
	v_mul_f32_e32 v18, 0xbfb8aa3b, v136
	v_mul_f32_e32 v17, 0xbfb8aa3b, v137
	v_exp_f32_e32 v18, v18
	v_exp_f32_e32 v17, v17
	v_mul_f32_e32 v19, 0xbfb8aa3b, v152
	v_add_f32_e32 v16, v106, v107
	v_exp_f32_e32 v19, v19
	v_mul_f32_e32 v106, 0xbfb8aa3b, v153
	v_exp_f32_e32 v106, v106
	v_mul_f32_e32 v107, 0xbfb8aa3b, v218
	v_fmac_f32_e32 v135, v112, v112
	v_add_f32_e32 v16, v16, v126
	v_add_f32_e32 v18, 1.0, v18
	v_exp_f32_e32 v107, v107
	v_mul_f32_e32 v112, 0xbfb8aa3b, v217
	v_add_f32_e32 v16, v16, v127
	v_add_f32_e32 v17, 1.0, v17
	v_rcp_f32_e32 v18, v18
	v_exp_f32_e32 v112, v112
	v_rcp_f32_e32 v17, v17
	v_add_f32_e32 v19, 1.0, v19
	v_mul_f32_e32 v126, 0xbfb8aa3b, v16
	v_rcp_f32_e32 v19, v19
	v_add_f32_e32 v106, 1.0, v106
	v_exp_f32_e32 v126, v126
	v_rcp_f32_e32 v106, v106
	v_add_f32_e32 v107, 1.0, v107
	v_mul_f32_e32 v18, v136, v18
	v_rcp_f32_e32 v107, v107
	v_add_f32_e32 v112, 1.0, v112
	v_mul_f32_e32 v17, v137, v17
	v_mul_f32_e32 v136, v18, v18
	v_rcp_f32_e32 v112, v112
	v_fmac_f32_e32 v136, v17, v17
	v_mul_f32_e32 v19, v152, v19
	v_add_f32_e32 v126, 1.0, v126
	v_fmac_f32_e32 v136, v19, v19
	v_mul_f32_e32 v106, v153, v106
	v_rcp_f32_e32 v126, v126
	v_fmac_f32_e32 v136, v106, v106
	v_mul_f32_e32 v107, v218, v107
	v_fmac_f32_e32 v136, v107, v107
	v_mul_f32_e32 v112, v217, v112
	v_fmac_f32_e32 v136, v112, v112
	v_mul_f32_e32 v113, v132, v113
	v_fmac_f32_e32 v136, v113, v113
	v_mul_f32_e32 v126, v16, v126
	v_cvt_pk_bf16_f32 v16, v17, v18
	v_cvt_pk_bf16_f32 v17, v19, v106
	v_cvt_pk_bf16_f32 v18, v107, v112
	v_cvt_pk_bf16_f32 v19, v113, v126
	v_lshlrev_b32_e32 v113, 16, v129
	v_lshlrev_b32_e32 v112, 16, v128
	ds_write_b128 v169, v[16:19] offset:544
	v_pk_mov_b32 v[16:17], v[86:87], v[112:113] op_sel:[1,0]
	v_pk_mul_f32 v[18:19], v[24:25], v[112:113]
	v_pk_mul_f32 v[86:87], v[64:65], v[16:17]
	v_pk_mul_f32 v[16:17], v[24:25], v[16:17]
	v_lshlrev_b32_e32 v107, 16, v131
	v_add_f32_e32 v16, v68, v16
	v_add_f32_e32 v16, v16, v17
	v_mul_f32_e32 v17, 0xbfb8aa3b, v16
	v_exp_f32_e32 v17, v17
	v_and_b32_e32 v68, 0xffff0000, v128
	v_pk_mul_f32 v[84:85], v[10:11], v[104:105]
	v_fmac_f32_e32 v136, v126, v126
	v_add_f32_e32 v17, 1.0, v17
	v_rcp_f32_e32 v17, v17
	v_pk_mul_f32 v[126:127], v[64:65], v[112:113]
	v_mul_f32_e32 v106, v16, v17
	v_add_f32_e32 v16, v116, v117
	v_add_f32_e32 v16, v16, v18
	v_add_f32_e32 v116, v16, v19
	v_pk_mov_b32 v[16:17], v[92:93], v[68:69] op_sel:[1,0]
	v_pk_mul_f32 v[18:19], v[4:5], v[68:69]
	v_pk_mul_f32 v[92:93], v[12:13], v[16:17]
	v_pk_mul_f32 v[16:17], v[4:5], v[16:17]
	s_nop 0
	v_add_f32_e32 v16, v70, v16
	v_add_f32_e32 v16, v16, v17
	v_mul_f32_e32 v17, 0xbfb8aa3b, v16
	v_exp_f32_e32 v17, v17
	v_pk_mul_f32 v[70:71], v[12:13], v[68:69]
	v_add_f32_e32 v17, 1.0, v17
	v_rcp_f32_e32 v17, v17
	s_nop 0
	v_mul_f32_e32 v16, v16, v17
	v_mul_f32_e32 v137, v16, v16
	v_add_f32_e32 v17, v94, v95
	v_fmac_f32_e32 v137, v106, v106
	v_cvt_pk_bf16_f32 v16, v106, v16
	v_add_f32_e32 v17, v17, v18
	v_lshlrev_b32_e32 v106, 16, v130
	v_add_f32_e32 v117, v17, v19
	v_pk_mov_b32 v[18:19], v[108:109], v[106:107] op_sel:[1,0]
	v_add_f32_e32 v17, v72, v73
	v_pk_mul_f32 v[94:95], v[62:63], v[18:19]
	v_pk_mul_f32 v[18:19], v[20:21], v[18:19]
	v_pk_mul_f32 v[108:109], v[20:21], v[106:107]
	v_add_f32_e32 v17, v17, v18
	v_add_f32_e32 v17, v17, v19
	v_mul_f32_e32 v18, 0xbfb8aa3b, v17
	v_exp_f32_e32 v18, v18
	v_and_b32_e32 v73, 0xffff0000, v131
	v_and_b32_e32 v72, 0xffff0000, v130
	v_pk_mul_f32 v[128:129], v[62:63], v[106:107]
	v_add_f32_e32 v18, 1.0, v18
	v_rcp_f32_e32 v18, v18
	s_nop 0
	v_mul_f32_e32 v17, v17, v18
	v_add_f32_e32 v18, v118, v119
	v_add_f32_e32 v18, v18, v108
	v_add_f32_e32 v118, v18, v109
	v_pk_mov_b32 v[18:19], v[96:97], v[72:73] op_sel:[1,0]
	v_fmac_f32_e32 v137, v17, v17
	v_pk_mul_f32 v[96:97], v[14:15], v[18:19]
	v_pk_mul_f32 v[18:19], v[6:7], v[18:19]
	v_pk_mul_f32 v[108:109], v[6:7], v[72:73]
	v_add_f32_e32 v18, v74, v18
	v_add_f32_e32 v18, v18, v19
	v_mul_f32_e32 v19, 0xbfb8aa3b, v18
	v_exp_f32_e32 v19, v19
	v_pk_mul_f32 v[74:75], v[14:15], v[72:73]
	v_add_f32_e32 v19, 1.0, v19
	v_rcp_f32_e32 v19, v19
	s_nop 0
	v_mul_f32_e32 v18, v18, v19
	v_fmac_f32_e32 v137, v18, v18
	v_cvt_pk_bf16_f32 v17, v17, v18
	v_add_f32_e32 v18, v98, v99
	v_add_f32_e32 v18, v18, v108
	v_add_f32_e32 v119, v18, v109
	v_lshlrev_b32_e32 v109, 16, v125
	v_lshlrev_b32_e32 v108, 16, v124
	v_pk_mov_b32 v[18:19], v[114:115], v[108:109] op_sel:[1,0]
	v_pk_mul_f32 v[114:115], v[22:23], v[108:109]
	v_pk_mul_f32 v[98:99], v[30:31], v[18:19]
	v_pk_mul_f32 v[18:19], v[22:23], v[18:19]
	v_lshlrev_b32_e32 v125, 16, v216
	v_add_f32_e32 v18, v76, v18
	v_add_f32_e32 v18, v18, v19
	v_mul_f32_e32 v19, 0xbfb8aa3b, v18
	v_exp_f32_e32 v19, v19
	v_and_b32_e32 v76, 0xffff0000, v124
	v_lshlrev_b32_e32 v124, 16, v191
	v_pk_mul_f32 v[130:131], v[30:31], v[108:109]
	v_add_f32_e32 v19, 1.0, v19
	v_rcp_f32_e32 v19, v19
	s_nop 0
	v_mul_f32_e32 v132, v18, v19
	v_add_f32_e32 v18, v120, v121
	v_add_f32_e32 v18, v18, v114
	v_add_f32_e32 v152, v18, v115
	v_pk_mov_b32 v[18:19], v[100:101], v[76:77] op_sel:[1,0]
	v_pk_mul_f32 v[114:115], v[0:1], v[76:77]
	v_pk_mul_f32 v[100:101], v[8:9], v[18:19]
	v_pk_mul_f32 v[18:19], v[0:1], v[18:19]
	v_fmac_f32_e32 v137, v132, v132
	v_add_f32_e32 v18, v78, v18
	v_add_f32_e32 v18, v18, v19
	v_mul_f32_e32 v19, 0xbfb8aa3b, v18
	v_exp_f32_e32 v19, v19
	v_pk_mul_f32 v[78:79], v[8:9], v[76:77]
	v_add_f32_e32 v19, 1.0, v19
	v_rcp_f32_e32 v19, v19
	s_nop 0
	v_mul_f32_e32 v18, v18, v19
	v_add_f32_e32 v19, v102, v103
	v_add_f32_e32 v19, v19, v114
	v_pk_mov_b32 v[102:103], v[110:111], v[124:125] op_sel:[1,0]
	v_add_f32_e32 v153, v19, v115
	v_pk_mul_f32 v[110:111], v[28:29], v[102:103]
	v_pk_mul_f32 v[102:103], v[26:27], v[102:103]
	v_add_f32_e32 v19, v80, v81
	v_add_f32_e32 v19, v19, v102
	v_add_f32_e32 v19, v19, v103
	v_mul_f32_e32 v80, 0xbfb8aa3b, v19
	v_exp_f32_e32 v80, v80
	v_pk_mul_f32 v[114:115], v[26:27], v[124:125]
	v_and_b32_e32 v81, 0xffff0000, v216
	v_fmac_f32_e32 v137, v18, v18
	v_add_f32_e32 v80, 1.0, v80
	v_rcp_f32_e32 v80, v80
	v_cvt_pk_bf16_f32 v18, v132, v18
	v_pk_mul_f32 v[132:133], v[28:29], v[124:125]
	v_mul_f32_e32 v19, v19, v80
	v_add_f32_e32 v80, v122, v123
	v_add_f32_e32 v80, v80, v114
	v_add_f32_e32 v114, v80, v115
	v_and_b32_e32 v80, 0xffff0000, v191
	v_pk_mov_b32 v[102:103], v[104:105], v[80:81] op_sel:[1,0]
	v_fmac_f32_e32 v137, v19, v19
	v_pk_mul_f32 v[120:121], v[10:11], v[102:103]
	v_pk_mul_f32 v[102:103], v[2:3], v[102:103]
	v_pk_mul_f32 v[104:105], v[2:3], v[80:81]
	v_add_f32_e32 v82, v82, v102
	v_add_f32_e32 v82, v82, v103
	v_mul_f32_e32 v83, 0xbfb8aa3b, v82
	v_exp_f32_e32 v83, v83
	v_lshlrev_b32_e32 v103, 16, v213
	v_pk_mul_f32 v[122:123], v[10:11], v[80:81]
	v_add_f32_e32 v120, v120, v121
	v_add_f32_e32 v83, 1.0, v83
	v_rcp_f32_e32 v83, v83
	s_nop 0
	v_mul_f32_e32 v82, v82, v83
	v_cvt_pk_bf16_f32 v19, v19, v82
	ds_write_b128 v169, v[16:19] offset:816
	v_add_f32_e32 v16, v84, v85
	v_add_f32_e32 v16, v16, v104
	v_mul_f32_e32 v18, 0xbfb8aa3b, v117
	v_add_f32_e32 v16, v16, v105
	v_mul_f32_e32 v17, 0xbfb8aa3b, v116
	v_exp_f32_e32 v18, v18
	v_fmac_f32_e32 v137, v82, v82
	v_exp_f32_e32 v17, v17
	v_mul_f32_e32 v19, 0xbfb8aa3b, v118
	v_mul_f32_e32 v82, 0xbfb8aa3b, v119
	v_mul_f32_e32 v102, 0xbfb8aa3b, v16
	v_exp_f32_e32 v19, v19
	v_exp_f32_e32 v82, v82
	v_mul_f32_e32 v83, 0xbfb8aa3b, v152
	v_mul_f32_e32 v84, 0xbfb8aa3b, v153
	v_mul_f32_e32 v85, 0xbfb8aa3b, v114
	v_exp_f32_e32 v102, v102
	v_exp_f32_e32 v83, v83
	v_exp_f32_e32 v84, v84
	v_exp_f32_e32 v85, v85
	v_add_f32_e32 v18, 1.0, v18
	v_add_f32_e32 v17, 1.0, v17
	v_rcp_f32_e32 v18, v18
	v_rcp_f32_e32 v17, v17
	v_add_f32_e32 v19, 1.0, v19
	v_add_f32_e32 v82, 1.0, v82
	v_add_f32_e32 v102, 1.0, v102
	v_rcp_f32_e32 v19, v19
	v_rcp_f32_e32 v82, v82
	v_add_f32_e32 v83, 1.0, v83
	v_add_f32_e32 v84, 1.0, v84
	v_add_f32_e32 v85, 1.0, v85
	v_rcp_f32_e32 v102, v102
	v_rcp_f32_e32 v83, v83
	v_rcp_f32_e32 v84, v84
	v_rcp_f32_e32 v85, v85
	v_mul_f32_e32 v18, v117, v18
	v_mul_f32_e32 v17, v116, v17
	v_mul_f32_e32 v191, v18, v18
	v_fmac_f32_e32 v191, v17, v17
	v_mul_f32_e32 v19, v118, v19
	v_mul_f32_e32 v82, v119, v82
	v_mul_f32_e32 v102, v16, v102
	v_cvt_pk_bf16_f32 v16, v17, v18
	v_cvt_pk_bf16_f32 v17, v19, v82
	v_lshlrev_b32_e32 v119, 16, v215
	v_lshlrev_b32_e32 v118, 16, v192
	v_fmac_f32_e32 v191, v19, v19
	v_mul_f32_e32 v83, v152, v83
	v_mul_f32_e32 v84, v153, v84
	v_mul_f32_e32 v85, v114, v85
	v_cvt_pk_bf16_f32 v18, v83, v84
	v_cvt_pk_bf16_f32 v19, v85, v102
	ds_write_b128 v169, v[16:19] offset:1088
	v_pk_mov_b32 v[16:17], v[112:113], v[118:119] op_sel:[1,0]
	v_fmac_f32_e32 v191, v82, v82
	v_pk_mul_f32 v[116:117], v[64:65], v[16:17]
	v_pk_mul_f32 v[16:17], v[24:25], v[16:17]
	v_add_f32_e32 v82, v86, v87
	v_add_f32_e32 v16, v82, v16
	v_add_f32_e32 v16, v16, v17
	v_mul_f32_e32 v17, 0xbfb8aa3b, v16
	v_exp_f32_e32 v17, v17
	v_pk_mul_f32 v[18:19], v[24:25], v[118:119]
	v_and_b32_e32 v113, 0xffff0000, v215
	v_and_b32_e32 v112, 0xffff0000, v192
	v_add_f32_e32 v17, 1.0, v17
	v_rcp_f32_e32 v17, v17
	v_fmac_f32_e32 v191, v83, v83
	v_add_f32_e32 v83, v92, v93
	v_lshlrev_b32_e32 v105, 16, v214
	v_mul_f32_e32 v82, v16, v17
	v_add_f32_e32 v16, v126, v127
	v_add_f32_e32 v16, v16, v18
	v_add_f32_e32 v126, v16, v19
	v_pk_mov_b32 v[16:17], v[68:69], v[112:113] op_sel:[1,0]
	v_pk_mul_f32 v[18:19], v[4:5], v[112:113]
	v_pk_mul_f32 v[68:69], v[12:13], v[16:17]
	v_pk_mul_f32 v[16:17], v[4:5], v[16:17]
	v_lshlrev_b32_e32 v104, 16, v212
	v_add_f32_e32 v16, v83, v16
	v_add_f32_e32 v16, v16, v17
	v_mul_f32_e32 v17, 0xbfb8aa3b, v16
	v_exp_f32_e32 v17, v17
	v_and_b32_e32 v87, 0xffff0000, v214
	v_and_b32_e32 v86, 0xffff0000, v212
	v_add_f32_e32 v92, v96, v97
	v_add_f32_e32 v17, 1.0, v17
	v_rcp_f32_e32 v17, v17
	v_fmac_f32_e32 v191, v84, v84
	v_fmac_f32_e32 v191, v85, v85
	v_fmac_f32_e32 v191, v102, v102
	v_mul_f32_e32 v16, v16, v17
	v_add_f32_e32 v17, v70, v71
	v_add_f32_e32 v17, v17, v18
	v_add_f32_e32 v127, v17, v19
	v_pk_mov_b32 v[18:19], v[106:107], v[104:105] op_sel:[1,0]
	v_add_f32_e32 v17, v94, v95
	v_pk_mul_f32 v[70:71], v[62:63], v[18:19]
	v_pk_mul_f32 v[18:19], v[20:21], v[18:19]
	v_mul_f32_e32 v192, v16, v16
	v_add_f32_e32 v17, v17, v18
	v_add_f32_e32 v17, v17, v19
	v_mul_f32_e32 v18, 0xbfb8aa3b, v17
	v_exp_f32_e32 v18, v18
	v_fmac_f32_e32 v192, v82, v82
	v_cvt_pk_bf16_f32 v16, v82, v16
	v_pk_mul_f32 v[82:83], v[20:21], v[104:105]
	v_add_f32_e32 v18, 1.0, v18
	v_rcp_f32_e32 v18, v18
	v_lshlrev_b32_e32 v102, 16, v194
	v_add_f32_e32 v94, v98, v99
	v_and_b32_e32 v95, 0xffff0000, v213
	v_mul_f32_e32 v17, v17, v18
	v_add_f32_e32 v18, v128, v129
	v_add_f32_e32 v18, v18, v82
	v_add_f32_e32 v128, v18, v83
	v_pk_mov_b32 v[18:19], v[72:73], v[86:87] op_sel:[1,0]
	v_fmac_f32_e32 v192, v17, v17
	v_pk_mul_f32 v[72:73], v[14:15], v[18:19]
	v_pk_mul_f32 v[18:19], v[6:7], v[18:19]
	v_pk_mul_f32 v[82:83], v[6:7], v[86:87]
	v_add_f32_e32 v18, v92, v18
	v_add_f32_e32 v18, v18, v19
	v_mul_f32_e32 v19, 0xbfb8aa3b, v18
	v_exp_f32_e32 v19, v19
	v_add_f32_e32 v96, v100, v101
	v_lshlrev_b32_e32 v101, 16, v195
	v_lshlrev_b32_e32 v100, 16, v193
	v_add_f32_e32 v19, 1.0, v19
	v_rcp_f32_e32 v19, v19
	v_pk_mul_f32 v[114:115], v[64:65], v[118:119]
	v_pk_mul_f32 v[84:85], v[12:13], v[112:113]
	v_mul_f32_e32 v18, v18, v19
	v_fmac_f32_e32 v192, v18, v18
	v_cvt_pk_bf16_f32 v17, v17, v18
	v_add_f32_e32 v18, v74, v75
	v_add_f32_e32 v18, v18, v82
	v_add_f32_e32 v129, v18, v83
	v_pk_mov_b32 v[18:19], v[108:109], v[102:103] op_sel:[1,0]
	v_pk_mul_f32 v[82:83], v[22:23], v[102:103]
	v_pk_mul_f32 v[74:75], v[30:31], v[18:19]
	v_pk_mul_f32 v[18:19], v[22:23], v[18:19]
	v_pk_mul_f32 v[106:107], v[62:63], v[104:105]
	v_add_f32_e32 v18, v94, v18
	v_add_f32_e32 v18, v18, v19
	v_mul_f32_e32 v19, 0xbfb8aa3b, v18
	v_exp_f32_e32 v19, v19
	v_and_b32_e32 v94, 0xffff0000, v194
	v_pk_mul_f32 v[92:93], v[14:15], v[86:87]
	v_pk_mul_f32 v[108:109], v[30:31], v[102:103]
	v_add_f32_e32 v19, 1.0, v19
	v_rcp_f32_e32 v19, v19
	s_nop 0
	v_mul_f32_e32 v98, v18, v19
	v_add_f32_e32 v18, v130, v131
	v_add_f32_e32 v18, v18, v82
	v_add_f32_e32 v130, v18, v83
	v_pk_mov_b32 v[18:19], v[76:77], v[94:95] op_sel:[1,0]
	v_pk_mul_f32 v[82:83], v[0:1], v[94:95]
	v_pk_mul_f32 v[76:77], v[8:9], v[18:19]
	v_pk_mul_f32 v[18:19], v[0:1], v[18:19]
	v_fmac_f32_e32 v192, v98, v98
	v_add_f32_e32 v18, v96, v18
	v_add_f32_e32 v18, v18, v19
	v_mul_f32_e32 v19, 0xbfb8aa3b, v18
	v_exp_f32_e32 v19, v19
	v_mul_f32_e32 v121, 0xbfb8aa3b, v130
	v_exp_f32_e32 v121, v121
	v_pk_mul_f32 v[96:97], v[8:9], v[94:95]
	v_add_f32_e32 v19, 1.0, v19
	v_rcp_f32_e32 v19, v19
	v_add_f32_e32 v121, 1.0, v121
	v_rcp_f32_e32 v121, v121
	v_mul_f32_e32 v18, v18, v19
	v_add_f32_e32 v19, v78, v79
	v_add_f32_e32 v19, v19, v82
	v_add_f32_e32 v131, v19, v83
	v_pk_mov_b32 v[82:83], v[124:125], v[100:101] op_sel:[1,0]
	v_add_f32_e32 v19, v110, v111
	v_pk_mul_f32 v[78:79], v[28:29], v[82:83]
	v_pk_mul_f32 v[82:83], v[26:27], v[82:83]
	v_fmac_f32_e32 v192, v18, v18
	v_add_f32_e32 v19, v19, v82
	v_add_f32_e32 v19, v19, v83
	v_mul_f32_e32 v82, 0xbfb8aa3b, v19
	v_exp_f32_e32 v82, v82
	v_cvt_pk_bf16_f32 v18, v98, v18
	v_pk_mul_f32 v[98:99], v[26:27], v[100:101]
	v_mul_f32_e32 v121, v130, v121
	v_add_f32_e32 v82, 1.0, v82
	v_rcp_f32_e32 v82, v82
	v_pk_mul_f32 v[110:111], v[28:29], v[100:101]
	v_mul_f32_e32 v19, v19, v82
	v_add_f32_e32 v82, v132, v133
	v_add_f32_e32 v82, v82, v98
	v_add_f32_e32 v133, v82, v99
	v_and_b32_e32 v99, 0xffff0000, v195
	v_and_b32_e32 v98, 0xffff0000, v193
	v_pk_mov_b32 v[82:83], v[80:81], v[98:99] op_sel:[1,0]
	v_fmac_f32_e32 v192, v19, v19
	v_pk_mul_f32 v[80:81], v[10:11], v[82:83]
	v_pk_mul_f32 v[82:83], v[2:3], v[82:83]
	v_pk_mul_f32 v[124:125], v[2:3], v[98:99]
	v_add_f32_e32 v82, v120, v82
	v_add_f32_e32 v82, v82, v83
	v_mul_f32_e32 v83, 0xbfb8aa3b, v82
	v_exp_f32_e32 v83, v83
	s_nop 0
	v_add_f32_e32 v83, 1.0, v83
	v_rcp_f32_e32 v83, v83
	s_nop 0
	v_mul_f32_e32 v120, v82, v83
	v_cvt_pk_bf16_f32 v19, v19, v120
	ds_write_b128 v169, v[16:19] offset:1360
	v_mul_f32_e32 v18, 0xbfb8aa3b, v127
	v_mul_f32_e32 v17, 0xbfb8aa3b, v126
	v_exp_f32_e32 v18, v18
	v_exp_f32_e32 v17, v17
	v_mul_f32_e32 v19, 0xbfb8aa3b, v128
	v_fmac_f32_e32 v192, v120, v120
	v_exp_f32_e32 v19, v19
	v_mul_f32_e32 v120, 0xbfb8aa3b, v129
	v_add_f32_e32 v16, v122, v123
	v_exp_f32_e32 v120, v120
	v_add_f32_e32 v16, v16, v124
	v_add_f32_e32 v18, 1.0, v18
	v_mul_f32_e32 v122, 0xbfb8aa3b, v131
	v_add_f32_e32 v16, v16, v125
	v_add_f32_e32 v17, 1.0, v17
	v_rcp_f32_e32 v18, v18
	v_exp_f32_e32 v122, v122
	v_mul_f32_e32 v123, 0xbfb8aa3b, v133
	v_rcp_f32_e32 v17, v17
	v_add_f32_e32 v19, 1.0, v19
	v_exp_f32_e32 v123, v123
	v_mul_f32_e32 v124, 0xbfb8aa3b, v16
	v_rcp_f32_e32 v19, v19
	v_add_f32_e32 v120, 1.0, v120
	v_exp_f32_e32 v124, v124
	v_rcp_f32_e32 v120, v120
	v_mul_f32_e32 v18, v127, v18
	v_add_f32_e32 v122, 1.0, v122
	v_mul_f32_e32 v17, v126, v17
	v_mul_f32_e32 v132, v18, v18
	v_rcp_f32_e32 v122, v122
	v_add_f32_e32 v123, 1.0, v123
	v_fmac_f32_e32 v132, v17, v17
	v_mul_f32_e32 v19, v128, v19
	v_rcp_f32_e32 v123, v123
	v_add_f32_e32 v124, 1.0, v124
	v_fmac_f32_e32 v132, v19, v19
	v_mul_f32_e32 v120, v129, v120
	v_rcp_f32_e32 v124, v124
	v_fmac_f32_e32 v132, v120, v120
	v_fmac_f32_e32 v132, v121, v121
	v_mul_f32_e32 v122, v131, v122
	v_fmac_f32_e32 v132, v122, v122
	v_mul_f32_e32 v123, v133, v123
	v_fmac_f32_e32 v132, v123, v123
	v_mul_f32_e32 v124, v16, v124
	v_fmac_f32_e32 v132, v124, v124
	v_pk_mul_f32 v[82:83], v[10:11], v[98:99]
	v_cvt_pk_bf16_f32 v16, v17, v18
	v_cvt_pk_bf16_f32 v17, v19, v120
	v_cvt_pk_bf16_f32 v18, v121, v122
	v_cvt_pk_bf16_f32 v19, v123, v124
	ds_write_b128 v169, v[16:19] offset:1632
	s_mov_b32 s28, 0x130df000
	v_add_f32_e32 v114, v114, v115
	v_add_f32_e32 v116, v116, v117
	v_add_f32_e32 v70, v70, v71
	v_add_f32_e32 v74, v74, v75
	v_add_f32_e32 v78, v78, v79
	s_waitcnt vmcnt(0)
	v_cndmask_b32_e64 v122, v223, 0, s[48:49]
	v_cndmask_b32_e64 v123, v222, 0, s[48:49]
	v_cndmask_b32_e64 v124, v221, 0, s[48:49]
	v_cndmask_b32_e64 v125, v220, 0, s[48:49]
	v_cndmask_b32_e64 v16, v224, 0, s[48:49]
	v_cndmask_b32_e64 v17, v225, 0, s[48:49]
	v_cndmask_b32_e64 v18, v226, 0, s[48:49]
	v_cndmask_b32_e64 v19, v227, 0, s[48:49]
	v_cndmask_b32_e64 v212, v229, 0, s[66:67]
	v_cndmask_b32_e64 v213, v228, 0, s[66:67]
	v_cndmask_b32_e64 v195, v230, 0, s[66:67]
	v_cndmask_b32_e64 v194, v231, 0, s[66:67]
	v_cndmask_b32_e64 v223, v235, 0, s[48:49]
	v_cndmask_b32_e64 v225, v234, 0, s[48:49]
	v_cndmask_b32_e64 v227, v233, 0, s[48:49]
	v_cndmask_b32_e64 v229, v232, 0, s[48:49]
	v_cndmask_b32_e64 v224, v239, 0, s[48:49]
	v_cndmask_b32_e64 v226, v238, 0, s[48:49]
	v_cndmask_b32_e64 v228, v237, 0, s[48:49]
	v_cndmask_b32_e64 v230, v236, 0, s[48:49]
	v_cndmask_b32_e64 v231, v245, 0, s[48:49]
	v_cndmask_b32_e64 v233, v244, 0, s[48:49]
	v_cndmask_b32_e64 v235, v243, 0, s[48:49]
	v_cndmask_b32_e64 v214, v242, 0, s[48:49]
	v_add_co_u32_e32 v120, vcc, 0x130d7000, v66
	s_nop 1
	v_addc_co_u32_e32 v121, vcc, 0, v67, vcc
	global_load_dwordx4 v[242:245], v[120:121], off offset:2560
	v_cndmask_b32_e64 v232, v249, 0, s[48:49]
	v_cndmask_b32_e64 v234, v248, 0, s[48:49]
	v_cndmask_b32_e64 v236, v247, 0, s[48:49]
	v_cndmask_b32_e64 v237, v246, 0, s[48:49]
	v_add_co_u32_e32 v120, vcc, 0x130db000, v66
	s_nop 1
	v_addc_co_u32_e32 v121, vcc, 0, v67, vcc
	global_load_dwordx4 v[246:249], v[120:121], off offset:3072
	v_and_b32_e32 v115, 0xffff0000, v125
	s_waitcnt vmcnt(1)
	v_cndmask_b32_e64 v215, v245, 0, s[62:63]
	v_cndmask_b32_e64 v217, v244, 0, s[62:63]
	v_cndmask_b32_e64 v219, v243, 0, s[62:63]
	v_cndmask_b32_e64 v221, v242, 0, s[62:63]
	v_lshlrev_b32_e32 v121, 16, v125
	s_waitcnt vmcnt(0)
	v_cndmask_b32_e64 v216, v249, 0, s[64:65]
	v_cndmask_b32_e64 v218, v248, 0, s[64:65]
	v_cndmask_b32_e64 v220, v247, 0, s[64:65]
	v_cndmask_b32_e64 v222, v246, 0, s[64:65]
	v_cndmask_b32_e64 v16, v16, 0, s[48:49]
	v_lshlrev_b32_e32 v120, 16, v16
	v_pk_mov_b32 v[118:119], v[118:119], v[120:121] op_sel:[1,0]
	v_cndmask_b32_e64 v17, v17, 0, s[48:49]
	v_pk_mul_f32 v[66:67], v[64:65], v[118:119]
	v_pk_mul_f32 v[118:119], v[24:25], v[118:119]
	v_cndmask_b32_e64 v18, v18, 0, s[48:49]
	v_add_f32_e32 v116, v116, v118
	v_add_f32_e32 v116, v116, v119
	v_mul_f32_e32 v117, 0xbfb8aa3b, v116
	v_exp_f32_e32 v117, v117
	v_cndmask_b32_e64 v19, v19, 0, s[48:49]
	v_add_f32_e32 v66, v66, v67
	v_add_f32_e32 v117, 1.0, v117
	v_rcp_f32_e32 v117, v117
	s_waitcnt vmcnt(0)
	s_nop 0
	s_nop 0
	v_pk_mul_f32 v[126:127], v[24:25], v[120:121]
	s_nop 0
	v_add_f32_e32 v114, v114, v126
	v_add_f32_e32 v193, v114, v127
	v_and_b32_e32 v114, 0xffff0000, v16
	v_pk_mov_b32 v[118:119], v[112:113], v[114:115] op_sel:[1,0]
	v_add_f32_e32 v16, v68, v69
	v_pk_mul_f32 v[112:113], v[12:13], v[118:119]
	v_pk_mul_f32 v[118:119], v[4:5], v[118:119]
	v_pk_mul_f32 v[126:127], v[4:5], v[114:115]
	v_add_f32_e32 v16, v16, v118
	v_add_f32_e32 v16, v16, v119
	v_mul_f32_e32 v68, 0xbfb8aa3b, v16
	v_exp_f32_e32 v68, v68
	v_mul_f32_e32 v128, v116, v117
	s_nop 0
	v_pk_mul_f32 v[116:117], v[64:65], v[120:121]
	v_add_f32_e32 v68, 1.0, v68
	v_rcp_f32_e32 v68, v68
	v_pk_mul_f32 v[118:119], v[12:13], v[114:115]
	v_mul_f32_e32 v16, v16, v68
	v_add_f32_e32 v68, v84, v85
	v_lshlrev_b32_e32 v85, 16, v124
	v_lshlrev_b32_e32 v84, 16, v17
	v_add_f32_e32 v68, v68, v126
	v_pk_mov_b32 v[104:105], v[104:105], v[84:85] op_sel:[1,0]
	v_add_f32_e32 v152, v68, v127
	v_pk_mul_f32 v[68:69], v[62:63], v[104:105]
	v_pk_mul_f32 v[104:105], v[20:21], v[104:105]
	v_mul_f32_e32 v133, v16, v16
	v_add_f32_e32 v70, v70, v104
	v_add_f32_e32 v70, v70, v105
	v_mul_f32_e32 v71, 0xbfb8aa3b, v70
	v_exp_f32_e32 v71, v71
	v_fmac_f32_e32 v133, v128, v128
	v_cvt_pk_bf16_f32 v16, v128, v16
	v_pk_mul_f32 v[128:129], v[20:21], v[84:85]
	v_add_f32_e32 v71, 1.0, v71
	v_rcp_f32_e32 v71, v71
	v_and_b32_e32 v105, 0xffff0000, v124
	v_and_b32_e32 v104, 0xffff0000, v17
	v_pk_mov_b32 v[86:87], v[86:87], v[104:105] op_sel:[1,0]
	v_mul_f32_e32 v125, v70, v71
	v_add_f32_e32 v70, v106, v107
	v_add_f32_e32 v70, v70, v128
	v_add_f32_e32 v153, v70, v129
	v_pk_mul_f32 v[70:71], v[14:15], v[86:87]
	v_pk_mul_f32 v[86:87], v[6:7], v[86:87]
	v_add_f32_e32 v17, v72, v73
	v_add_f32_e32 v17, v17, v86
	v_add_f32_e32 v17, v17, v87
	v_mul_f32_e32 v72, 0xbfb8aa3b, v17
	v_exp_f32_e32 v72, v72
	v_pk_mul_f32 v[106:107], v[6:7], v[104:105]
	v_fmac_f32_e32 v133, v125, v125
	v_pk_mul_f32 v[126:127], v[62:63], v[84:85]
	v_add_f32_e32 v72, 1.0, v72
	v_rcp_f32_e32 v72, v72
	v_add_f32_e32 v70, v70, v71
	v_pk_mul_f32 v[86:87], v[14:15], v[104:105]
	v_mul_f32_e32 v17, v17, v72
	v_add_f32_e32 v72, v92, v93
	v_add_f32_e32 v72, v72, v106
	v_add_f32_e32 v238, v72, v107
	v_lshlrev_b32_e32 v107, 16, v123
	v_lshlrev_b32_e32 v106, 16, v18
	v_pk_mov_b32 v[92:93], v[102:103], v[106:107] op_sel:[1,0]
	v_pk_mul_f32 v[102:103], v[22:23], v[106:107]
	v_pk_mul_f32 v[72:73], v[30:31], v[92:93]
	v_pk_mul_f32 v[92:93], v[22:23], v[92:93]
	v_fmac_f32_e32 v133, v17, v17
	v_add_f32_e32 v74, v74, v92
	v_add_f32_e32 v74, v74, v93
	v_mul_f32_e32 v75, 0xbfb8aa3b, v74
	v_exp_f32_e32 v75, v75
	v_and_b32_e32 v93, 0xffff0000, v123
	v_and_b32_e32 v92, 0xffff0000, v18
	v_pk_mov_b32 v[94:95], v[94:95], v[92:93] op_sel:[1,0]
	v_add_f32_e32 v75, 1.0, v75
	v_rcp_f32_e32 v75, v75
	v_add_f32_e32 v18, v76, v77
	v_cvt_pk_bf16_f32 v17, v125, v17
	v_lshlrev_b32_e32 v125, 16, v122
	v_mul_f32_e32 v124, v74, v75
	v_add_f32_e32 v74, v108, v109
	v_add_f32_e32 v74, v74, v102
	v_add_f32_e32 v108, v74, v103
	v_pk_mul_f32 v[74:75], v[8:9], v[94:95]
	v_pk_mul_f32 v[94:95], v[0:1], v[94:95]
	v_fmac_f32_e32 v133, v124, v124
	v_add_f32_e32 v18, v18, v94
	v_add_f32_e32 v18, v18, v95
	v_mul_f32_e32 v76, 0xbfb8aa3b, v18
	v_exp_f32_e32 v76, v76
	v_pk_mul_f32 v[102:103], v[0:1], v[92:93]
	v_lshlrev_b32_e32 v123, 16, v237
	v_add_f32_e32 v72, v72, v73
	v_add_f32_e32 v76, 1.0, v76
	v_rcp_f32_e32 v76, v76
	v_pk_mul_f32 v[128:129], v[30:31], v[106:107]
	v_add_f32_e32 v74, v74, v75
	v_pk_mul_f32 v[94:95], v[8:9], v[92:93]
	v_mul_f32_e32 v18, v18, v76
	v_fmac_f32_e32 v133, v18, v18
	v_cvt_pk_bf16_f32 v18, v124, v18
	v_add_f32_e32 v76, v96, v97
	v_lshlrev_b32_e32 v124, 16, v19
	v_add_f32_e32 v76, v76, v102
	v_pk_mov_b32 v[96:97], v[100:101], v[124:125] op_sel:[1,0]
	v_add_f32_e32 v102, v76, v103
	v_pk_mul_f32 v[76:77], v[28:29], v[96:97]
	v_pk_mul_f32 v[96:97], v[26:27], v[96:97]
	v_pk_mul_f32 v[100:101], v[26:27], v[124:125]
	v_add_f32_e32 v78, v78, v96
	v_add_f32_e32 v78, v78, v97
	v_mul_f32_e32 v79, 0xbfb8aa3b, v78
	v_exp_f32_e32 v79, v79
	v_and_b32_e32 v97, 0xffff0000, v122
	v_and_b32_e32 v96, 0xffff0000, v19
	v_pk_mov_b32 v[98:99], v[98:99], v[96:97] op_sel:[1,0]
	v_add_f32_e32 v79, 1.0, v79
	v_rcp_f32_e32 v79, v79
	v_add_f32_e32 v19, v80, v81
	v_lshlrev_b32_e32 v122, 16, v214
	v_pk_mul_f32 v[130:131], v[28:29], v[124:125]
	v_mul_f32_e32 v103, v78, v79
	v_add_f32_e32 v78, v110, v111
	v_add_f32_e32 v78, v78, v100
	v_add_f32_e32 v109, v78, v101
	v_pk_mul_f32 v[78:79], v[10:11], v[98:99]
	v_pk_mul_f32 v[98:99], v[2:3], v[98:99]
	v_fmac_f32_e32 v133, v103, v103
	v_add_f32_e32 v19, v19, v98
	v_add_f32_e32 v19, v19, v99
	v_mul_f32_e32 v80, 0xbfb8aa3b, v19
	v_exp_f32_e32 v80, v80
	v_pk_mul_f32 v[100:101], v[2:3], v[96:97]
	v_mul_f32_e32 v98, 0xbfb8aa3b, v102
	v_mul_f32_e32 v99, 0xbfb8aa3b, v109
	v_add_f32_e32 v80, 1.0, v80
	v_rcp_f32_e32 v80, v80
	v_exp_f32_e32 v98, v98
	v_exp_f32_e32 v99, v99
	v_lshlrev_b32_e32 v111, 16, v236
	v_mul_f32_e32 v19, v19, v80
	v_fmac_f32_e32 v133, v19, v19
	v_cvt_pk_bf16_f32 v19, v103, v19
	ds_write_b128 v169, v[16:19] offset:1904
	v_add_f32_e32 v16, v82, v83
	v_mul_f32_e32 v18, 0xbfb8aa3b, v152
	v_add_f32_e32 v16, v16, v100
	v_mul_f32_e32 v17, 0xbfb8aa3b, v193
	v_exp_f32_e32 v18, v18
	v_add_f32_e32 v16, v16, v101
	v_exp_f32_e32 v17, v17
	v_mul_f32_e32 v19, 0xbfb8aa3b, v153
	v_exp_f32_e32 v19, v19
	v_mul_f32_e32 v82, 0xbfb8aa3b, v238
	v_mul_f32_e32 v100, 0xbfb8aa3b, v16
	v_exp_f32_e32 v82, v82
	v_mul_f32_e32 v83, 0xbfb8aa3b, v108
	v_exp_f32_e32 v100, v100
	v_add_f32_e32 v18, 1.0, v18
	v_exp_f32_e32 v83, v83
	v_add_f32_e32 v17, 1.0, v17
	v_rcp_f32_e32 v18, v18
	v_rcp_f32_e32 v17, v17
	v_add_f32_e32 v19, 1.0, v19
	v_rcp_f32_e32 v19, v19
	v_add_f32_e32 v82, 1.0, v82
	v_add_f32_e32 v100, 1.0, v100
	v_rcp_f32_e32 v82, v82
	v_add_f32_e32 v83, 1.0, v83
	v_add_f32_e32 v98, 1.0, v98
	v_add_f32_e32 v99, 1.0, v99
	v_rcp_f32_e32 v100, v100
	v_mul_f32_e32 v18, v152, v18
	v_rcp_f32_e32 v83, v83
	v_rcp_f32_e32 v98, v98
	v_rcp_f32_e32 v99, v99
	v_mul_f32_e32 v17, v193, v17
	v_mul_f32_e32 v193, v18, v18
	v_fmac_f32_e32 v193, v17, v17
	v_mul_f32_e32 v19, v153, v19
	v_fmac_f32_e32 v193, v19, v19
	v_mul_f32_e32 v82, v238, v82
	v_mul_f32_e32 v100, v16, v100
	v_cvt_pk_bf16_f32 v16, v17, v18
	v_cvt_pk_bf16_f32 v17, v19, v82
	v_fmac_f32_e32 v193, v82, v82
	v_mul_f32_e32 v83, v108, v83
	v_mul_f32_e32 v98, v102, v98
	v_mul_f32_e32 v99, v109, v99
	v_cvt_pk_bf16_f32 v18, v83, v98
	v_cvt_pk_bf16_f32 v19, v99, v100
	ds_write_b128 v169, v[16:19] offset:2176
	v_pk_mov_b32 v[16:17], v[120:121], v[122:123] op_sel:[1,0]
	v_fmac_f32_e32 v193, v83, v83
	v_pk_mul_f32 v[82:83], v[64:65], v[16:17]
	v_pk_mul_f32 v[16:17], v[24:25], v[16:17]
	v_fmac_f32_e32 v193, v98, v98
	v_add_f32_e32 v16, v66, v16
	v_add_f32_e32 v16, v16, v17
	v_mul_f32_e32 v17, 0xbfb8aa3b, v16
	v_exp_f32_e32 v17, v17
	v_pk_mul_f32 v[18:19], v[24:25], v[122:123]
	v_fmac_f32_e32 v193, v99, v99
	v_and_b32_e32 v99, 0xffff0000, v237
	v_add_f32_e32 v17, 1.0, v17
	v_rcp_f32_e32 v17, v17
	v_and_b32_e32 v98, 0xffff0000, v214
	v_fmac_f32_e32 v193, v100, v100
	v_add_f32_e32 v100, v112, v113
	v_mul_f32_e32 v102, v16, v17
	v_add_f32_e32 v16, v116, v117
	v_add_f32_e32 v16, v16, v18
	v_add_f32_e32 v238, v16, v19
	v_pk_mov_b32 v[16:17], v[114:115], v[98:99] op_sel:[1,0]
	v_pk_mul_f32 v[18:19], v[4:5], v[98:99]
	v_pk_mul_f32 v[66:67], v[12:13], v[16:17]
	v_pk_mul_f32 v[16:17], v[4:5], v[16:17]
	v_lshlrev_b32_e32 v110, 16, v235
	v_add_f32_e32 v16, v100, v16
	v_add_f32_e32 v16, v16, v17
	v_mul_f32_e32 v17, 0xbfb8aa3b, v16
	v_exp_f32_e32 v17, v17
	v_pk_mul_f32 v[80:81], v[10:11], v[96:97]
	v_add_f32_e32 v78, v78, v79
	v_add_f32_e32 v17, 1.0, v17
	v_rcp_f32_e32 v17, v17
	v_add_f32_e32 v82, v82, v83
	v_pk_mul_f32 v[120:121], v[64:65], v[122:123]
	v_add_f32_e32 v66, v66, v67
	v_mul_f32_e32 v16, v16, v17
	v_add_f32_e32 v17, v118, v119
	v_add_f32_e32 v17, v17, v18
	v_add_f32_e32 v152, v17, v19
	v_pk_mov_b32 v[18:19], v[84:85], v[110:111] op_sel:[1,0]
	v_add_f32_e32 v17, v68, v69
	v_pk_mul_f32 v[84:85], v[62:63], v[18:19]
	v_pk_mul_f32 v[18:19], v[20:21], v[18:19]
	v_mul_f32_e32 v214, v16, v16
	v_add_f32_e32 v17, v17, v18
	v_add_f32_e32 v17, v17, v19
	v_mul_f32_e32 v18, 0xbfb8aa3b, v17
	v_exp_f32_e32 v18, v18
	v_fmac_f32_e32 v214, v102, v102
	v_cvt_pk_bf16_f32 v16, v102, v16
	v_pk_mul_f32 v[102:103], v[20:21], v[110:111]
	v_add_f32_e32 v18, 1.0, v18
	v_rcp_f32_e32 v18, v18
	v_pk_mul_f32 v[100:101], v[12:13], v[98:99]
	v_pk_mul_f32 v[112:113], v[62:63], v[110:111]
	v_mul_f32_e32 v17, v17, v18
	v_add_f32_e32 v18, v126, v127
	v_add_f32_e32 v18, v18, v102
	v_add_f32_e32 v127, v18, v103
	v_and_b32_e32 v103, 0xffff0000, v236
	v_and_b32_e32 v102, 0xffff0000, v235
	v_pk_mov_b32 v[18:19], v[104:105], v[102:103] op_sel:[1,0]
	v_fmac_f32_e32 v214, v17, v17
	v_pk_mul_f32 v[68:69], v[14:15], v[18:19]
	v_pk_mul_f32 v[18:19], v[6:7], v[18:19]
	v_pk_mul_f32 v[108:109], v[6:7], v[102:103]
	v_add_f32_e32 v18, v70, v18
	v_add_f32_e32 v18, v18, v19
	v_mul_f32_e32 v19, 0xbfb8aa3b, v18
	v_exp_f32_e32 v19, v19
	v_add_f32_e32 v68, v68, v69
	v_pk_mul_f32 v[104:105], v[14:15], v[102:103]
	v_add_f32_e32 v19, 1.0, v19
	v_rcp_f32_e32 v19, v19
	s_nop 0
	v_mul_f32_e32 v18, v18, v19
	v_fmac_f32_e32 v214, v18, v18
	v_cvt_pk_bf16_f32 v17, v17, v18
	v_add_f32_e32 v18, v86, v87
	v_add_f32_e32 v18, v18, v108
	v_add_f32_e32 v153, v18, v109
	v_lshlrev_b32_e32 v109, 16, v234
	v_lshlrev_b32_e32 v108, 16, v233
	v_pk_mov_b32 v[18:19], v[106:107], v[108:109] op_sel:[1,0]
	v_pk_mul_f32 v[86:87], v[22:23], v[108:109]
	v_pk_mul_f32 v[70:71], v[30:31], v[18:19]
	v_pk_mul_f32 v[18:19], v[22:23], v[18:19]
	v_add_f32_e32 v70, v70, v71
	v_add_f32_e32 v18, v72, v18
	v_add_f32_e32 v18, v18, v19
	v_mul_f32_e32 v19, 0xbfb8aa3b, v18
	v_exp_f32_e32 v19, v19
	v_pk_mul_f32 v[114:115], v[30:31], v[108:109]
	v_add_f32_e32 v19, 1.0, v19
	v_rcp_f32_e32 v19, v19
	s_nop 0
	v_mul_f32_e32 v116, v18, v19
	v_add_f32_e32 v18, v128, v129
	v_add_f32_e32 v18, v18, v86
	v_add_f32_e32 v128, v18, v87
	v_and_b32_e32 v87, 0xffff0000, v234
	v_and_b32_e32 v86, 0xffff0000, v233
	v_pk_mov_b32 v[18:19], v[92:93], v[86:87] op_sel:[1,0]
	v_pk_mul_f32 v[106:107], v[0:1], v[86:87]
	v_pk_mul_f32 v[72:73], v[8:9], v[18:19]
	v_pk_mul_f32 v[18:19], v[0:1], v[18:19]
	v_fmac_f32_e32 v214, v116, v116
	v_add_f32_e32 v18, v74, v18
	v_add_f32_e32 v18, v18, v19
	v_mul_f32_e32 v19, 0xbfb8aa3b, v18
	v_exp_f32_e32 v19, v19
	v_add_f32_e32 v72, v72, v73
	v_pk_mul_f32 v[92:93], v[8:9], v[86:87]
	v_add_f32_e32 v19, 1.0, v19
	v_rcp_f32_e32 v19, v19
	s_nop 0
	v_mul_f32_e32 v18, v18, v19
	v_add_f32_e32 v19, v94, v95
	v_add_f32_e32 v19, v19, v106
	v_add_f32_e32 v129, v19, v107
	v_lshlrev_b32_e32 v107, 16, v232
	v_lshlrev_b32_e32 v106, 16, v231
	v_pk_mov_b32 v[94:95], v[124:125], v[106:107] op_sel:[1,0]
	v_add_f32_e32 v19, v76, v77
	v_pk_mul_f32 v[74:75], v[28:29], v[94:95]
	v_pk_mul_f32 v[94:95], v[26:27], v[94:95]
	v_pk_mul_f32 v[118:119], v[26:27], v[106:107]
	v_add_f32_e32 v19, v19, v94
	v_add_f32_e32 v19, v19, v95
	v_mul_f32_e32 v76, 0xbfb8aa3b, v19
	v_exp_f32_e32 v76, v76
	v_and_b32_e32 v95, 0xffff0000, v232
	v_and_b32_e32 v94, 0xffff0000, v231
	v_pk_mov_b32 v[96:97], v[96:97], v[94:95] op_sel:[1,0]
	v_add_f32_e32 v76, 1.0, v76
	v_rcp_f32_e32 v76, v76
	v_fmac_f32_e32 v214, v18, v18
	v_cvt_pk_bf16_f32 v18, v116, v18
	v_pk_mul_f32 v[116:117], v[28:29], v[106:107]
	v_mul_f32_e32 v19, v19, v76
	v_add_f32_e32 v76, v130, v131
	v_add_f32_e32 v76, v76, v118
	v_add_f32_e32 v124, v76, v119
	v_pk_mul_f32 v[76:77], v[10:11], v[96:97]
	v_pk_mul_f32 v[96:97], v[2:3], v[96:97]
	v_fmac_f32_e32 v214, v19, v19
	v_add_f32_e32 v78, v78, v96
	v_add_f32_e32 v78, v78, v97
	v_mul_f32_e32 v79, 0xbfb8aa3b, v78
	v_exp_f32_e32 v79, v79
	v_pk_mul_f32 v[118:119], v[2:3], v[94:95]
	v_mul_f32_e32 v97, 0xbfb8aa3b, v124
	v_exp_f32_e32 v97, v97
	v_add_f32_e32 v79, 1.0, v79
	v_rcp_f32_e32 v79, v79
	v_add_f32_e32 v76, v76, v77
	v_add_f32_e32 v97, 1.0, v97
	v_rcp_f32_e32 v97, v97
	v_mul_f32_e32 v96, v78, v79
	v_cvt_pk_bf16_f32 v19, v19, v96
	ds_write_b128 v169, v[16:19] offset:2448
	v_mul_f32_e32 v18, 0xbfb8aa3b, v152
	v_mul_f32_e32 v17, 0xbfb8aa3b, v238
	v_exp_f32_e32 v18, v18
	v_exp_f32_e32 v17, v17
	v_mul_f32_e32 v19, 0xbfb8aa3b, v127
	v_add_f32_e32 v16, v80, v81
	v_exp_f32_e32 v19, v19
	v_mul_f32_e32 v80, 0xbfb8aa3b, v153
	v_exp_f32_e32 v80, v80
	v_mul_f32_e32 v81, 0xbfb8aa3b, v128
	v_fmac_f32_e32 v214, v96, v96
	v_add_f32_e32 v16, v16, v118
	v_add_f32_e32 v18, 1.0, v18
	v_exp_f32_e32 v81, v81
	v_mul_f32_e32 v96, 0xbfb8aa3b, v129
	v_add_f32_e32 v16, v16, v119
	v_add_f32_e32 v17, 1.0, v17
	v_rcp_f32_e32 v18, v18
	v_exp_f32_e32 v96, v96
	v_rcp_f32_e32 v17, v17
	v_add_f32_e32 v19, 1.0, v19
	v_mul_f32_e32 v118, 0xbfb8aa3b, v16
	v_rcp_f32_e32 v19, v19
	v_add_f32_e32 v80, 1.0, v80
	v_exp_f32_e32 v118, v118
	v_rcp_f32_e32 v80, v80
	v_add_f32_e32 v81, 1.0, v81
	v_mul_f32_e32 v18, v152, v18
	v_rcp_f32_e32 v81, v81
	v_add_f32_e32 v96, 1.0, v96
	v_mul_f32_e32 v17, v238, v17
	v_mul_f32_e32 v126, v18, v18
	v_rcp_f32_e32 v96, v96
	v_fmac_f32_e32 v126, v17, v17
	v_mul_f32_e32 v19, v127, v19
	v_add_f32_e32 v118, 1.0, v118
	v_fmac_f32_e32 v126, v19, v19
	v_mul_f32_e32 v80, v153, v80
	v_rcp_f32_e32 v118, v118
	v_fmac_f32_e32 v126, v80, v80
	v_mul_f32_e32 v81, v128, v81
	v_fmac_f32_e32 v126, v81, v81
	v_mul_f32_e32 v96, v129, v96
	v_fmac_f32_e32 v126, v96, v96
	v_mul_f32_e32 v97, v124, v97
	v_fmac_f32_e32 v126, v97, v97
	v_mul_f32_e32 v118, v16, v118
	v_cvt_pk_bf16_f32 v16, v17, v18
	v_cvt_pk_bf16_f32 v17, v19, v80
	v_cvt_pk_bf16_f32 v18, v81, v96
	v_cvt_pk_bf16_f32 v19, v97, v118
	v_lshlrev_b32_e32 v97, 16, v230
	v_lshlrev_b32_e32 v96, 16, v229
	ds_write_b128 v169, v[16:19] offset:2720
	v_pk_mov_b32 v[16:17], v[122:123], v[96:97] op_sel:[1,0]
	v_pk_mul_f32 v[18:19], v[24:25], v[96:97]
	v_pk_mul_f32 v[80:81], v[64:65], v[16:17]
	v_pk_mul_f32 v[16:17], v[24:25], v[16:17]
	v_fmac_f32_e32 v126, v118, v118
	v_add_f32_e32 v16, v82, v16
	v_add_f32_e32 v16, v16, v17
	v_mul_f32_e32 v17, 0xbfb8aa3b, v16
	v_exp_f32_e32 v17, v17
	v_and_b32_e32 v119, 0xffff0000, v230
	v_and_b32_e32 v118, 0xffff0000, v229
	v_pk_mul_f32 v[78:79], v[10:11], v[94:95]
	v_add_f32_e32 v17, 1.0, v17
	v_rcp_f32_e32 v17, v17
	v_pk_mul_f32 v[122:123], v[64:65], v[96:97]
	v_mul_f32_e32 v124, v16, v17
	v_add_f32_e32 v16, v120, v121
	v_add_f32_e32 v16, v16, v18
	v_add_f32_e32 v128, v16, v19
	v_pk_mov_b32 v[16:17], v[98:99], v[118:119] op_sel:[1,0]
	v_pk_mul_f32 v[18:19], v[4:5], v[118:119]
	v_pk_mul_f32 v[82:83], v[12:13], v[16:17]
	v_pk_mul_f32 v[16:17], v[4:5], v[16:17]
	v_lshlrev_b32_e32 v99, 16, v228
	v_add_f32_e32 v16, v66, v16
	v_add_f32_e32 v16, v16, v17
	v_mul_f32_e32 v17, 0xbfb8aa3b, v16
	v_exp_f32_e32 v17, v17
	v_lshlrev_b32_e32 v98, 16, v227
	v_pk_mul_f32 v[120:121], v[12:13], v[118:119]
	v_add_f32_e32 v17, 1.0, v17
	v_rcp_f32_e32 v17, v17
	s_nop 0
	v_mul_f32_e32 v16, v16, v17
	v_add_f32_e32 v17, v100, v101
	v_add_f32_e32 v17, v17, v18
	v_add_f32_e32 v129, v17, v19
	v_pk_mov_b32 v[18:19], v[110:111], v[98:99] op_sel:[1,0]
	v_add_f32_e32 v17, v84, v85
	v_pk_mul_f32 v[66:67], v[62:63], v[18:19]
	v_pk_mul_f32 v[18:19], v[20:21], v[18:19]
	v_pk_mul_f32 v[100:101], v[20:21], v[98:99]
	v_add_f32_e32 v17, v17, v18
	v_add_f32_e32 v17, v17, v19
	v_mul_f32_e32 v18, 0xbfb8aa3b, v17
	v_exp_f32_e32 v18, v18
	v_mul_f32_e32 v127, v16, v16
	v_fmac_f32_e32 v127, v124, v124
	v_cvt_pk_bf16_f32 v16, v124, v16
	v_add_f32_e32 v18, 1.0, v18
	v_rcp_f32_e32 v18, v18
	v_pk_mul_f32 v[124:125], v[62:63], v[98:99]
	v_mul_f32_e32 v17, v17, v18
	v_add_f32_e32 v18, v112, v113
	v_add_f32_e32 v18, v18, v100
	v_add_f32_e32 v130, v18, v101
	v_and_b32_e32 v101, 0xffff0000, v228
	v_and_b32_e32 v100, 0xffff0000, v227
	v_pk_mov_b32 v[18:19], v[102:103], v[100:101] op_sel:[1,0]
	v_fmac_f32_e32 v127, v17, v17
	v_pk_mul_f32 v[84:85], v[14:15], v[18:19]
	v_pk_mul_f32 v[18:19], v[6:7], v[18:19]
	v_pk_mul_f32 v[102:103], v[6:7], v[100:101]
	v_add_f32_e32 v18, v68, v18
	v_add_f32_e32 v18, v18, v19
	v_mul_f32_e32 v19, 0xbfb8aa3b, v18
	v_exp_f32_e32 v19, v19
	v_pk_mul_f32 v[110:111], v[14:15], v[100:101]
	v_add_f32_e32 v19, 1.0, v19
	v_rcp_f32_e32 v19, v19
	s_nop 0
	v_mul_f32_e32 v18, v18, v19
	v_fmac_f32_e32 v127, v18, v18
	v_cvt_pk_bf16_f32 v17, v17, v18
	v_add_f32_e32 v18, v104, v105
	v_add_f32_e32 v18, v18, v102
	v_add_f32_e32 v131, v18, v103
	v_lshlrev_b32_e32 v103, 16, v226
	v_lshlrev_b32_e32 v102, 16, v225
	v_pk_mov_b32 v[18:19], v[108:109], v[102:103] op_sel:[1,0]
	v_pk_mul_f32 v[104:105], v[22:23], v[102:103]
	v_pk_mul_f32 v[68:69], v[30:31], v[18:19]
	v_pk_mul_f32 v[18:19], v[22:23], v[18:19]
	v_pk_mul_f32 v[112:113], v[30:31], v[102:103]
	v_add_f32_e32 v18, v70, v18
	v_add_f32_e32 v18, v18, v19
	v_mul_f32_e32 v19, 0xbfb8aa3b, v18
	v_exp_f32_e32 v19, v19
	v_add_f32_e32 v68, v68, v69
	v_and_b32_e32 v69, 0xffff0000, v218
	v_add_f32_e32 v19, 1.0, v19
	v_rcp_f32_e32 v19, v19
	s_nop 0
	v_mul_f32_e32 v152, v18, v19
	v_add_f32_e32 v18, v114, v115
	v_add_f32_e32 v18, v18, v104
	v_add_f32_e32 v153, v18, v105
	v_and_b32_e32 v105, 0xffff0000, v226
	v_and_b32_e32 v104, 0xffff0000, v225
	v_pk_mov_b32 v[18:19], v[86:87], v[104:105] op_sel:[1,0]
	v_pk_mul_f32 v[86:87], v[0:1], v[104:105]
	v_pk_mul_f32 v[70:71], v[8:9], v[18:19]
	v_pk_mul_f32 v[18:19], v[0:1], v[18:19]
	v_fmac_f32_e32 v127, v152, v152
	v_add_f32_e32 v18, v72, v18
	v_add_f32_e32 v18, v18, v19
	v_mul_f32_e32 v19, 0xbfb8aa3b, v18
	v_exp_f32_e32 v19, v19
	v_pk_mul_f32 v[108:109], v[8:9], v[104:105]
	v_add_f32_e32 v19, 1.0, v19
	v_rcp_f32_e32 v19, v19
	s_nop 0
	v_mul_f32_e32 v18, v18, v19
	v_add_f32_e32 v19, v92, v93
	v_add_f32_e32 v19, v19, v86
	v_fmac_f32_e32 v127, v18, v18
	v_cvt_pk_bf16_f32 v18, v152, v18
	v_add_f32_e32 v152, v19, v87
	v_lshlrev_b32_e32 v87, 16, v224
	v_lshlrev_b32_e32 v86, 16, v223
	v_pk_mov_b32 v[92:93], v[106:107], v[86:87] op_sel:[1,0]
	v_add_f32_e32 v19, v74, v75
	v_pk_mul_f32 v[72:73], v[28:29], v[92:93]
	v_pk_mul_f32 v[92:93], v[26:27], v[92:93]
	v_pk_mul_f32 v[114:115], v[26:27], v[86:87]
	v_add_f32_e32 v19, v19, v92
	v_add_f32_e32 v19, v19, v93
	v_mul_f32_e32 v74, 0xbfb8aa3b, v19
	v_exp_f32_e32 v74, v74
	v_and_b32_e32 v93, 0xffff0000, v224
	v_and_b32_e32 v92, 0xffff0000, v223
	v_pk_mov_b32 v[94:95], v[94:95], v[92:93] op_sel:[1,0]
	v_add_f32_e32 v74, 1.0, v74
	v_rcp_f32_e32 v74, v74
	v_pk_mul_f32 v[106:107], v[28:29], v[86:87]
	v_mul_f32_e32 v19, v19, v74
	v_add_f32_e32 v74, v116, v117
	v_add_f32_e32 v74, v74, v114
	v_add_f32_e32 v116, v74, v115
	v_pk_mul_f32 v[74:75], v[10:11], v[94:95]
	v_pk_mul_f32 v[94:95], v[2:3], v[94:95]
	v_fmac_f32_e32 v127, v19, v19
	v_add_f32_e32 v76, v76, v94
	v_add_f32_e32 v76, v76, v95
	v_mul_f32_e32 v77, 0xbfb8aa3b, v76
	v_exp_f32_e32 v77, v77
	v_pk_mul_f32 v[114:115], v[2:3], v[92:93]
	v_mul_f32_e32 v95, 0xbfb8aa3b, v152
	v_exp_f32_e32 v95, v95
	v_add_f32_e32 v77, 1.0, v77
	v_rcp_f32_e32 v77, v77
	v_add_f32_e32 v95, 1.0, v95
	v_rcp_f32_e32 v95, v95
	v_mul_f32_e32 v94, v76, v77
	v_cvt_pk_bf16_f32 v19, v19, v94
	ds_write_b128 v169, v[16:19] offset:2992
	v_add_f32_e32 v16, v78, v79
	v_mul_f32_e32 v18, 0xbfb8aa3b, v129
	v_add_f32_e32 v16, v16, v114
	v_mul_f32_e32 v17, 0xbfb8aa3b, v128
	v_exp_f32_e32 v18, v18
	v_add_f32_e32 v16, v16, v115
	v_exp_f32_e32 v17, v17
	v_mul_f32_e32 v19, 0xbfb8aa3b, v130
	v_exp_f32_e32 v19, v19
	v_mul_f32_e32 v78, 0xbfb8aa3b, v131
	v_mul_f32_e32 v115, 0xbfb8aa3b, v16
	v_exp_f32_e32 v78, v78
	v_mul_f32_e32 v79, 0xbfb8aa3b, v153
	v_mul_f32_e32 v114, 0xbfb8aa3b, v116
	v_exp_f32_e32 v115, v115
	v_add_f32_e32 v18, 1.0, v18
	v_exp_f32_e32 v79, v79
	v_exp_f32_e32 v114, v114
	v_add_f32_e32 v17, 1.0, v17
	v_rcp_f32_e32 v18, v18
	v_rcp_f32_e32 v17, v17
	v_add_f32_e32 v19, 1.0, v19
	v_rcp_f32_e32 v19, v19
	v_add_f32_e32 v78, 1.0, v78
	v_add_f32_e32 v115, 1.0, v115
	v_rcp_f32_e32 v78, v78
	v_add_f32_e32 v79, 1.0, v79
	v_add_f32_e32 v114, 1.0, v114
	v_rcp_f32_e32 v115, v115
	v_mul_f32_e32 v18, v129, v18
	v_rcp_f32_e32 v79, v79
	v_rcp_f32_e32 v114, v114
	v_fmac_f32_e32 v127, v94, v94
	v_mul_f32_e32 v17, v128, v17
	v_mul_f32_e32 v94, v18, v18
	v_fmac_f32_e32 v94, v17, v17
	v_mul_f32_e32 v19, v130, v19
	v_fmac_f32_e32 v94, v19, v19
	v_mul_f32_e32 v78, v131, v78
	v_mul_f32_e32 v115, v16, v115
	v_cvt_pk_bf16_f32 v16, v17, v18
	v_cvt_pk_bf16_f32 v17, v19, v78
	v_fmac_f32_e32 v94, v78, v78
	v_mul_f32_e32 v79, v153, v79
	v_mul_f32_e32 v95, v152, v95
	v_mul_f32_e32 v114, v116, v114
	v_cvt_pk_bf16_f32 v18, v79, v95
	v_cvt_pk_bf16_f32 v19, v114, v115
	ds_write_b128 v169, v[16:19] offset:3264
	v_lshlrev_b32_e32 v16, 16, v221
	v_lshlrev_b32_e32 v17, 16, v222
	v_fmac_f32_e32 v94, v79, v79
	v_pk_mov_b32 v[78:79], v[96:97], v[16:17] op_sel:[1,0]
	v_fmac_f32_e32 v94, v95, v95
	v_pk_mul_f32 v[18:19], v[64:65], v[78:79]
	v_pk_mul_f32 v[64:65], v[24:25], v[16:17]
	v_pk_mul_f32 v[78:79], v[24:25], v[78:79]
	v_add_f32_e32 v16, v80, v81
	v_add_f32_e32 v16, v16, v78
	v_add_f32_e32 v16, v16, v79
	v_mul_f32_e32 v78, 0xbfb8aa3b, v16
	v_exp_f32_e32 v78, v78
	v_fmac_f32_e32 v94, v114, v114
	v_pk_mul_f32 v[76:77], v[10:11], v[92:93]
	v_fmac_f32_e32 v94, v115, v115
	v_add_f32_e32 v78, 1.0, v78
	v_rcp_f32_e32 v78, v78
	s_nop 0
	v_mul_f32_e32 v114, v16, v78
	v_add_f32_e32 v16, v122, v123
	v_add_f32_e32 v16, v16, v64
	v_add_f32_e32 v95, v16, v65
	v_and_b32_e32 v65, 0xffff0000, v222
	v_and_b32_e32 v64, 0xffff0000, v221
	v_pk_mov_b32 v[80:81], v[118:119], v[64:65] op_sel:[1,0]
	v_add_f32_e32 v16, v82, v83
	v_pk_mul_f32 v[78:79], v[12:13], v[80:81]
	v_pk_mul_f32 v[12:13], v[4:5], v[80:81]
	v_pk_mul_f32 v[96:97], v[4:5], v[64:65]
	v_add_f32_e32 v12, v16, v12
	v_add_f32_e32 v12, v12, v13
	v_mul_f32_e32 v13, 0xbfb8aa3b, v12
	v_exp_f32_e32 v13, v13
	v_lshlrev_b32_e32 v80, 16, v219
	v_lshlrev_b32_e32 v81, 16, v220
	v_pk_mov_b32 v[82:83], v[98:99], v[80:81] op_sel:[1,0]
	v_add_f32_e32 v13, 1.0, v13
	v_rcp_f32_e32 v13, v13
	v_pk_mul_f32 v[62:63], v[62:63], v[82:83]
	v_pk_mul_f32 v[82:83], v[20:21], v[82:83]
	v_lshlrev_b32_e32 v99, 16, v194
	v_mul_f32_e32 v12, v12, v13
	v_add_f32_e32 v13, v120, v121
	v_add_f32_e32 v13, v13, v96
	v_add_f32_e32 v64, v13, v97
	v_add_f32_e32 v13, v66, v67
	v_add_f32_e32 v13, v13, v82
	v_add_f32_e32 v13, v13, v83
	v_mul_f32_e32 v66, 0xbfb8aa3b, v13
	v_exp_f32_e32 v66, v66
	v_pk_mul_f32 v[96:97], v[20:21], v[80:81]
	v_and_b32_e32 v67, 0xffff0000, v220
	v_mul_f32_e32 v16, v12, v12
	v_add_f32_e32 v66, 1.0, v66
	v_rcp_f32_e32 v66, v66
	v_fmac_f32_e32 v16, v114, v114
	v_cvt_pk_bf16_f32 v12, v114, v12
	v_mul_f32_e32 v13, v13, v66
	v_add_f32_e32 v66, v124, v125
	v_add_f32_e32 v66, v66, v96
	v_add_f32_e32 v80, v66, v97
	v_and_b32_e32 v66, 0xffff0000, v219
	v_pk_mov_b32 v[96:97], v[100:101], v[66:67] op_sel:[1,0]
	v_fmac_f32_e32 v16, v13, v13
	v_pk_mul_f32 v[82:83], v[14:15], v[96:97]
	v_pk_mul_f32 v[14:15], v[6:7], v[66:67]
	v_pk_mul_f32 v[96:97], v[6:7], v[96:97]
	v_add_f32_e32 v66, v84, v85
	v_add_f32_e32 v66, v66, v96
	v_add_f32_e32 v66, v66, v97
	v_mul_f32_e32 v84, 0xbfb8aa3b, v66
	v_exp_f32_e32 v84, v84
	v_lshlrev_b32_e32 v85, 16, v218
	v_and_b32_e32 v101, 0xffff0000, v194
	v_add_f32_e32 v84, 1.0, v84
	v_rcp_f32_e32 v84, v84
	s_nop 0
	v_mul_f32_e32 v66, v66, v84
	v_fmac_f32_e32 v16, v66, v66
	v_cvt_pk_bf16_f32 v13, v13, v66
	v_add_f32_e32 v66, v110, v111
	v_add_f32_e32 v14, v66, v14
	v_lshlrev_b32_e32 v84, 16, v217
	v_add_f32_e32 v66, v14, v15
	v_pk_mov_b32 v[14:15], v[102:103], v[84:85] op_sel:[1,0]
	v_pk_mul_f32 v[96:97], v[22:23], v[84:85]
	v_pk_mul_f32 v[30:31], v[30:31], v[14:15]
	v_pk_mul_f32 v[14:15], v[22:23], v[14:15]
	s_nop 0
	v_add_f32_e32 v14, v68, v14
	v_add_f32_e32 v14, v14, v15
	v_mul_f32_e32 v15, 0xbfb8aa3b, v14
	v_exp_f32_e32 v15, v15
	v_and_b32_e32 v68, 0xffff0000, v217
	v_add_f32_e32 v15, 1.0, v15
	v_rcp_f32_e32 v15, v15
	s_nop 0
	v_mul_f32_e32 v84, v14, v15
	v_add_f32_e32 v14, v112, v113
	v_add_f32_e32 v14, v14, v96
	v_add_f32_e32 v98, v14, v97
	v_pk_mov_b32 v[14:15], v[104:105], v[68:69] op_sel:[1,0]
	v_pk_mul_f32 v[96:97], v[0:1], v[68:69]
	v_pk_mul_f32 v[8:9], v[8:9], v[14:15]
	v_pk_mul_f32 v[14:15], v[0:1], v[14:15]
	v_add_f32_e32 v68, v70, v71
	v_add_f32_e32 v14, v68, v14
	v_add_f32_e32 v14, v14, v15
	v_mul_f32_e32 v15, 0xbfb8aa3b, v14
	v_exp_f32_e32 v15, v15
	v_lshlrev_b32_e32 v70, 16, v215
	v_lshlrev_b32_e32 v71, 16, v216
	v_pk_mov_b32 v[86:87], v[86:87], v[70:71] op_sel:[1,0]
	v_add_f32_e32 v15, 1.0, v15
	v_rcp_f32_e32 v15, v15
	v_pk_mul_f32 v[28:29], v[28:29], v[86:87]
	v_pk_mul_f32 v[86:87], v[26:27], v[86:87]
	v_fmac_f32_e32 v16, v84, v84
	v_mul_f32_e32 v14, v14, v15
	v_add_f32_e32 v15, v108, v109
	v_add_f32_e32 v15, v15, v96
	v_add_f32_e32 v68, v15, v97
	v_add_f32_e32 v15, v72, v73
	v_add_f32_e32 v15, v15, v86
	v_and_b32_e32 v73, 0xffff0000, v216
	v_and_b32_e32 v72, 0xffff0000, v215
	v_add_f32_e32 v15, v15, v87
	v_pk_mov_b32 v[86:87], v[92:93], v[72:73] op_sel:[1,0]
	v_pk_mul_f32 v[92:93], v[2:3], v[72:73]
	v_pk_mul_f32 v[10:11], v[10:11], v[86:87]
	v_pk_mul_f32 v[86:87], v[2:3], v[86:87]
	v_add_f32_e32 v72, v74, v75
	v_add_f32_e32 v72, v72, v86
	v_pk_mul_f32 v[96:97], v[26:27], v[70:71]
	v_mul_f32_e32 v70, 0xbfb8aa3b, v15
	v_add_f32_e32 v72, v72, v87
	v_exp_f32_e32 v70, v70
	v_mul_f32_e32 v74, 0xbfb8aa3b, v72
	v_exp_f32_e32 v74, v74
	v_fmac_f32_e32 v16, v14, v14
	v_add_f32_e32 v70, 1.0, v70
	v_rcp_f32_e32 v70, v70
	v_add_f32_e32 v74, 1.0, v74
	v_rcp_f32_e32 v74, v74
	v_cvt_pk_bf16_f32 v14, v84, v14
	v_mul_f32_e32 v15, v15, v70
	v_fmac_f32_e32 v16, v15, v15
	v_mul_f32_e32 v72, v72, v74
	v_cvt_pk_bf16_f32 v15, v15, v72
	ds_write_b128 v169, v[12:15] offset:3536
	v_add_f32_e32 v12, v76, v77
	v_add_f32_e32 v12, v12, v92
	v_add_f32_e32 v13, v12, v93
	v_mul_f32_e32 v12, 0xbfb8aa3b, v95
	v_exp_f32_e32 v12, v12
	v_mul_f32_e32 v74, 0xbfb8aa3b, v68
	v_exp_f32_e32 v74, v74
	v_add_f32_e32 v70, v106, v107
	v_add_f32_e32 v12, 1.0, v12
	v_rcp_f32_e32 v12, v12
	v_add_f32_e32 v74, 1.0, v74
	v_rcp_f32_e32 v74, v74
	v_fmac_f32_e32 v16, v72, v72
	v_mul_f32_e32 v14, v95, v12
	v_mul_f32_e32 v12, 0xbfb8aa3b, v64
	v_exp_f32_e32 v12, v12
	v_mul_f32_e32 v72, 0xbfb8aa3b, v66
	v_add_f32_e32 v70, v70, v96
	v_exp_f32_e32 v72, v72
	v_add_f32_e32 v70, v70, v97
	v_add_f32_e32 v12, 1.0, v12
	v_mul_f32_e32 v68, v68, v74
	v_mul_f32_e32 v74, 0xbfb8aa3b, v70
	v_rcp_f32_e32 v12, v12
	v_exp_f32_e32 v74, v74
	v_add_f32_e32 v72, 1.0, v72
	v_rcp_f32_e32 v72, v72
	v_mul_f32_e32 v15, v64, v12
	v_mul_f32_e32 v64, 0xbfb8aa3b, v80
	v_add_f32_e32 v74, 1.0, v74
	v_exp_f32_e32 v64, v64
	v_rcp_f32_e32 v74, v74
	v_mul_f32_e32 v66, v66, v72
	v_mul_f32_e32 v72, 0xbfb8aa3b, v98
	v_exp_f32_e32 v72, v72
	v_add_f32_e32 v64, 1.0, v64
	v_mul_f32_e32 v70, v70, v74
	v_mul_f32_e32 v74, 0xbfb8aa3b, v13
	v_rcp_f32_e32 v64, v64
	v_exp_f32_e32 v74, v74
	v_add_f32_e32 v72, 1.0, v72
	v_rcp_f32_e32 v72, v72
	v_mul_f32_e32 v12, v15, v15
	v_fmac_f32_e32 v12, v14, v14
	v_mul_f32_e32 v64, v80, v64
	v_add_f32_e32 v74, 1.0, v74
	v_fmac_f32_e32 v12, v64, v64
	v_rcp_f32_e32 v74, v74
	v_fmac_f32_e32 v12, v66, v66
	v_mul_f32_e32 v72, v98, v72
	v_fmac_f32_e32 v12, v72, v72
	v_fmac_f32_e32 v12, v68, v68
	v_fmac_f32_e32 v12, v70, v70
	v_mul_f32_e32 v13, v13, v74
	v_cvt_pk_bf16_f32 v74, v14, v15
	v_cvt_pk_bf16_f32 v75, v64, v66
	v_lshlrev_b32_e32 v15, 16, v213
	v_mov_b32_e32 v14, v17
	v_fmac_f32_e32 v12, v13, v13
	v_cvt_pk_bf16_f32 v76, v72, v68
	v_cvt_pk_bf16_f32 v77, v70, v13
	ds_write_b128 v169, v[74:77] offset:3808
	v_and_b32_e32 v75, 0xffff0000, v213
	v_pk_mul_f32 v[14:15], v[24:25], v[14:15]
	v_add_f32_e32 v13, v18, v19
	v_mov_b32_e32 v74, v65
	v_add_f32_e32 v13, v13, v14
	v_pk_mul_f32 v[4:5], v[4:5], v[74:75]
	v_add_f32_e32 v14, v78, v79
	v_lshlrev_b32_e32 v77, 16, v212
	v_add_f32_e32 v4, v14, v4
	v_mov_b32_e32 v76, v81
	v_add_f32_e32 v13, v13, v15
	v_add_f32_e32 v14, v4, v5
	v_pk_mul_f32 v[4:5], v[20:21], v[76:77]
	v_add_f32_e32 v15, v62, v63
	v_and_b32_e32 v87, 0xffff0000, v212
	v_add_f32_e32 v4, v15, v4
	v_mov_b32_e32 v86, v67
	v_add_f32_e32 v15, v4, v5
	v_pk_mul_f32 v[4:5], v[6:7], v[86:87]
	v_add_f32_e32 v6, v82, v83
	v_lshlrev_b32_e32 v93, 16, v195
	v_add_f32_e32 v4, v6, v4
	v_mov_b32_e32 v92, v85
	v_add_f32_e32 v6, v4, v5
	v_pk_mul_f32 v[4:5], v[22:23], v[92:93]
	v_add_f32_e32 v7, v30, v31
	v_add_f32_e32 v4, v7, v4
	v_add_f32_e32 v4, v4, v5
	v_add_f32_e32 v5, v8, v9
	v_mul_f32_e32 v9, 0xbfb8aa3b, v6
	v_exp_f32_e32 v9, v9
	v_and_b32_e32 v97, 0xffff0000, v195
	v_mov_b32_e32 v96, v69
	v_pk_mul_f32 v[0:1], v[0:1], v[96:97]
	v_add_f32_e32 v9, 1.0, v9
	v_rcp_f32_e32 v9, v9
	v_add_f32_e32 v0, v5, v0
	v_mov_b32_e32 v98, v71
	v_add_f32_e32 v5, v0, v1
	v_mul_f32_e32 v6, v6, v9
	v_mul_f32_e32 v9, 0xbfb8aa3b, v4
	v_exp_f32_e32 v9, v9
	v_pk_mul_f32 v[0:1], v[26:27], v[98:99]
	v_add_f32_e32 v7, v28, v29
	v_add_f32_e32 v0, v7, v0
	v_add_f32_e32 v9, 1.0, v9
	v_rcp_f32_e32 v9, v9
	v_mov_b32_e32 v100, v73
	v_add_f32_e32 v7, v0, v1
	v_pk_mul_f32 v[0:1], v[2:3], v[100:101]
	v_mul_f32_e32 v4, v4, v9
	v_mul_f32_e32 v9, 0xbfb8aa3b, v5
	v_add_f32_e32 v2, v10, v11
	v_exp_f32_e32 v9, v9
	v_add_f32_e32 v0, v2, v0
	v_add_f32_e32 v1, v0, v1
	v_mul_f32_e32 v0, 0xbfb8aa3b, v13
	v_exp_f32_e32 v0, v0
	v_add_f32_e32 v9, 1.0, v9
	v_rcp_f32_e32 v9, v9
	v_mul_f32_e32 v8, 0xbfb8aa3b, v15
	v_add_f32_e32 v0, 1.0, v0
	v_rcp_f32_e32 v0, v0
	v_mul_f32_e32 v5, v5, v9
	v_mul_f32_e32 v9, 0xbfb8aa3b, v7
	v_exp_f32_e32 v9, v9
	v_mul_f32_e32 v2, v13, v0
	v_mul_f32_e32 v0, 0xbfb8aa3b, v14
	v_exp_f32_e32 v0, v0
	v_add_f32_e32 v9, 1.0, v9
	v_exp_f32_e32 v8, v8
	v_rcp_f32_e32 v9, v9
	v_add_f32_e32 v0, 1.0, v0
	v_rcp_f32_e32 v0, v0
	v_add_f32_e32 v8, 1.0, v8
	v_mul_f32_e32 v7, v7, v9
	v_mul_f32_e32 v9, 0xbfb8aa3b, v1
	v_rcp_f32_e32 v8, v8
	v_exp_f32_e32 v9, v9
	v_mul_f32_e32 v3, v14, v0
	v_mul_f32_e32 v0, v3, v3
	v_fmac_f32_e32 v0, v2, v2
	v_mul_f32_e32 v8, v15, v8
	v_add_f32_e32 v9, 1.0, v9
	v_fmac_f32_e32 v0, v8, v8
	v_rcp_f32_e32 v9, v9
	v_fmac_f32_e32 v0, v6, v6
	v_fmac_f32_e32 v0, v4, v4
	v_fmac_f32_e32 v0, v5, v5
	v_fmac_f32_e32 v0, v7, v7
	v_mul_f32_e32 v1, v1, v9
	v_fmac_f32_e32 v0, v1, v1
	v_cvt_pk_bf16_f32 v2, v2, v3
	v_cvt_pk_bf16_f32 v3, v8, v6
	v_cvt_pk_bf16_f32 v4, v4, v5
	v_cvt_pk_bf16_f32 v5, v7, v1
	ds_write_b128 v169, v[2:5] offset:4080
	v_readlane_b32 s8, v255, 7
	v_readlane_b32 s9, v255, 8
	s_andn2_b64 vcc, exec, s[8:9]
	s_cbranch_vccnz .LBB0_286
	v_and_b32_e32 v2, 64, v202
	v_add_u32_e32 v5, 64, v2
	v_xor_b32_e32 v1, 1, v202
	v_cmp_lt_i32_e32 vcc, v1, v5
	s_nop 1
	v_cndmask_b32_e32 v1, v202, v1, vcc
	v_lshlrev_b32_e32 v4, 2, v1
	v_xor_b32_e32 v1, 2, v202
	v_cmp_lt_i32_e32 vcc, v1, v5
	s_nop 1
	v_cndmask_b32_e32 v1, v202, v1, vcc
	v_lshlrev_b32_e32 v3, 2, v1
	v_xor_b32_e32 v1, 4, v202
	v_cmp_lt_i32_e32 vcc, v1, v5
	s_nop 1
	v_cndmask_b32_e32 v1, v202, v1, vcc
	v_lshlrev_b32_e32 v2, 2, v1
	v_xor_b32_e32 v1, 8, v202
	v_cmp_lt_i32_e32 vcc, v1, v5
	s_nop 1
	v_cndmask_b32_e32 v1, v202, v1, vcc
	v_lshlrev_b32_e32 v1, 2, v1
	ds_bpermute_b32 v20, v4, v134
	ds_bpermute_b32 v21, v4, v135
	ds_bpermute_b32 v22, v4, v136
	ds_bpermute_b32 v23, v4, v137
	ds_bpermute_b32 v24, v4, v191
	ds_bpermute_b32 v25, v4, v192
	ds_bpermute_b32 v26, v4, v132
	ds_bpermute_b32 v27, v4, v133
	s_waitcnt lgkmcnt(7)
	v_add_f32_e32 v134, v134, v20
	s_waitcnt lgkmcnt(6)
	v_add_f32_e32 v135, v135, v21
	s_waitcnt lgkmcnt(5)
	v_add_f32_e32 v136, v136, v22
	s_waitcnt lgkmcnt(4)
	v_add_f32_e32 v137, v137, v23
	s_waitcnt lgkmcnt(3)
	v_add_f32_e32 v191, v191, v24
	s_waitcnt lgkmcnt(2)
	v_add_f32_e32 v192, v192, v25
	s_waitcnt lgkmcnt(1)
	v_add_f32_e32 v132, v132, v26
	s_waitcnt lgkmcnt(0)
	v_add_f32_e32 v133, v133, v27
	ds_bpermute_b32 v20, v4, v193
	ds_bpermute_b32 v21, v4, v214
	ds_bpermute_b32 v22, v4, v126
	ds_bpermute_b32 v23, v4, v127
	ds_bpermute_b32 v24, v4, v94
	ds_bpermute_b32 v25, v4, v16
	ds_bpermute_b32 v26, v4, v12
	ds_bpermute_b32 v27, v4, v0
	s_waitcnt lgkmcnt(7)
	v_add_f32_e32 v193, v193, v20
	s_waitcnt lgkmcnt(6)
	v_add_f32_e32 v214, v214, v21
	s_waitcnt lgkmcnt(5)
	v_add_f32_e32 v126, v126, v22
	s_waitcnt lgkmcnt(4)
	v_add_f32_e32 v127, v127, v23
	s_waitcnt lgkmcnt(3)
	v_add_f32_e32 v94, v94, v24
	s_waitcnt lgkmcnt(2)
	v_add_f32_e32 v16, v16, v25
	s_waitcnt lgkmcnt(1)
	v_add_f32_e32 v12, v12, v26
	s_waitcnt lgkmcnt(0)
	v_add_f32_e32 v0, v0, v27
	ds_bpermute_b32 v20, v3, v134
	ds_bpermute_b32 v21, v3, v135
	ds_bpermute_b32 v22, v3, v136
	ds_bpermute_b32 v23, v3, v137
	ds_bpermute_b32 v24, v3, v191
	ds_bpermute_b32 v25, v3, v192
	ds_bpermute_b32 v26, v3, v132
	ds_bpermute_b32 v27, v3, v133
	s_waitcnt lgkmcnt(7)
	v_add_f32_e32 v134, v134, v20
	s_waitcnt lgkmcnt(6)
	v_add_f32_e32 v135, v135, v21
	s_waitcnt lgkmcnt(5)
	v_add_f32_e32 v136, v136, v22
	s_waitcnt lgkmcnt(4)
	v_add_f32_e32 v137, v137, v23
	s_waitcnt lgkmcnt(3)
	v_add_f32_e32 v191, v191, v24
	s_waitcnt lgkmcnt(2)
	v_add_f32_e32 v192, v192, v25
	s_waitcnt lgkmcnt(1)
	v_add_f32_e32 v132, v132, v26
	s_waitcnt lgkmcnt(0)
	v_add_f32_e32 v133, v133, v27
	ds_bpermute_b32 v20, v3, v193
	ds_bpermute_b32 v21, v3, v214
	ds_bpermute_b32 v22, v3, v126
	ds_bpermute_b32 v23, v3, v127
	ds_bpermute_b32 v24, v3, v94
	ds_bpermute_b32 v25, v3, v16
	ds_bpermute_b32 v26, v3, v12
	ds_bpermute_b32 v27, v3, v0
	s_waitcnt lgkmcnt(7)
	v_add_f32_e32 v193, v193, v20
	s_waitcnt lgkmcnt(6)
	v_add_f32_e32 v214, v214, v21
	s_waitcnt lgkmcnt(5)
	v_add_f32_e32 v126, v126, v22
	s_waitcnt lgkmcnt(4)
	v_add_f32_e32 v127, v127, v23
	s_waitcnt lgkmcnt(3)
	v_add_f32_e32 v94, v94, v24
	s_waitcnt lgkmcnt(2)
	v_add_f32_e32 v16, v16, v25
	s_waitcnt lgkmcnt(1)
	v_add_f32_e32 v12, v12, v26
	s_waitcnt lgkmcnt(0)
	v_add_f32_e32 v0, v0, v27
	ds_bpermute_b32 v20, v2, v134
	ds_bpermute_b32 v21, v2, v135
	ds_bpermute_b32 v22, v2, v136
	ds_bpermute_b32 v23, v2, v137
	ds_bpermute_b32 v24, v2, v191
	ds_bpermute_b32 v25, v2, v192
	ds_bpermute_b32 v26, v2, v132
	ds_bpermute_b32 v27, v2, v133
	s_waitcnt lgkmcnt(7)
	v_add_f32_e32 v134, v134, v20
	s_waitcnt lgkmcnt(6)
	v_add_f32_e32 v135, v135, v21
	s_waitcnt lgkmcnt(5)
	v_add_f32_e32 v136, v136, v22
	s_waitcnt lgkmcnt(4)
	v_add_f32_e32 v137, v137, v23
	s_waitcnt lgkmcnt(3)
	v_add_f32_e32 v191, v191, v24
	s_waitcnt lgkmcnt(2)
	v_add_f32_e32 v192, v192, v25
	s_waitcnt lgkmcnt(1)
	v_add_f32_e32 v132, v132, v26
	s_waitcnt lgkmcnt(0)
	v_add_f32_e32 v133, v133, v27
	ds_bpermute_b32 v20, v2, v193
	ds_bpermute_b32 v21, v2, v214
	ds_bpermute_b32 v22, v2, v126
	ds_bpermute_b32 v23, v2, v127
	ds_bpermute_b32 v24, v2, v94
	ds_bpermute_b32 v25, v2, v16
	ds_bpermute_b32 v26, v2, v12
	ds_bpermute_b32 v27, v2, v0
	s_waitcnt lgkmcnt(7)
	v_add_f32_e32 v193, v193, v20
	s_waitcnt lgkmcnt(6)
	v_add_f32_e32 v214, v214, v21
	s_waitcnt lgkmcnt(5)
	v_add_f32_e32 v126, v126, v22
	s_waitcnt lgkmcnt(4)
	v_add_f32_e32 v127, v127, v23
	s_waitcnt lgkmcnt(3)
	v_add_f32_e32 v94, v94, v24
	s_waitcnt lgkmcnt(2)
	v_add_f32_e32 v16, v16, v25
	s_waitcnt lgkmcnt(1)
	v_add_f32_e32 v12, v12, v26
	s_waitcnt lgkmcnt(0)
	v_add_f32_e32 v0, v0, v27
	ds_bpermute_b32 v20, v1, v134
	ds_bpermute_b32 v21, v1, v135
	ds_bpermute_b32 v22, v1, v136
	ds_bpermute_b32 v23, v1, v137
	ds_bpermute_b32 v24, v1, v191
	ds_bpermute_b32 v25, v1, v192
	ds_bpermute_b32 v26, v1, v132
	ds_bpermute_b32 v27, v1, v133
	s_waitcnt lgkmcnt(7)
	v_add_f32_e32 v134, v134, v20
	s_waitcnt lgkmcnt(6)
	v_add_f32_e32 v135, v135, v21
	s_waitcnt lgkmcnt(5)
	v_add_f32_e32 v136, v136, v22
	s_waitcnt lgkmcnt(4)
	v_add_f32_e32 v137, v137, v23
	s_waitcnt lgkmcnt(3)
	v_add_f32_e32 v191, v191, v24
	s_waitcnt lgkmcnt(2)
	v_add_f32_e32 v192, v192, v25
	s_waitcnt lgkmcnt(1)
	v_add_f32_e32 v132, v132, v26
	s_waitcnt lgkmcnt(0)
	v_add_f32_e32 v133, v133, v27
	ds_bpermute_b32 v20, v1, v193
	ds_bpermute_b32 v21, v1, v214
	ds_bpermute_b32 v22, v1, v126
	ds_bpermute_b32 v23, v1, v127
	ds_bpermute_b32 v24, v1, v94
	ds_bpermute_b32 v25, v1, v16
	ds_bpermute_b32 v26, v1, v12
	ds_bpermute_b32 v27, v1, v0
	s_waitcnt lgkmcnt(7)
	v_add_f32_e32 v193, v193, v20
	s_waitcnt lgkmcnt(6)
	v_add_f32_e32 v214, v214, v21
	s_waitcnt lgkmcnt(5)
	v_add_f32_e32 v126, v126, v22
	s_waitcnt lgkmcnt(4)
	v_add_f32_e32 v127, v127, v23
	s_waitcnt lgkmcnt(3)
	v_add_f32_e32 v94, v94, v24
	s_waitcnt lgkmcnt(2)
	v_add_f32_e32 v16, v16, v25
	s_waitcnt lgkmcnt(1)
	v_add_f32_e32 v12, v12, v26
	s_waitcnt lgkmcnt(0)
	v_add_f32_e32 v0, v0, v27
	v_cndmask_b32_e64 v5, 0, v134, s[6:7]
	v_readlane_b32 s8, v254, 20
	v_readlane_b32 s9, v254, 21
	s_nop 1
	v_cndmask_b32_e64 v5, v5, v135, s[8:9]
	v_readlane_b32 s8, v254, 22
	v_readlane_b32 s9, v254, 23
	s_nop 1
	v_cndmask_b32_e64 v5, v5, v136, s[8:9]
	v_readlane_b32 s8, v254, 24
	v_readlane_b32 s9, v254, 25
	s_nop 1
	v_cndmask_b32_e64 v5, v5, v137, s[8:9]
	v_readlane_b32 s8, v254, 26
	v_readlane_b32 s9, v254, 27
	s_nop 1
	v_cndmask_b32_e64 v5, v5, v191, s[8:9]
	v_readlane_b32 s8, v254, 28
	v_readlane_b32 s9, v254, 29
	s_nop 1
	v_cndmask_b32_e64 v5, v5, v192, s[8:9]
	v_readlane_b32 s8, v254, 30
	v_readlane_b32 s9, v254, 31
	s_nop 1
	v_cndmask_b32_e64 v5, v5, v132, s[8:9]
	v_readlane_b32 s8, v254, 32
	v_readlane_b32 s9, v254, 33
	s_nop 1
	v_cndmask_b32_e64 v5, v5, v133, s[8:9]
	v_readlane_b32 s8, v254, 34
	v_readlane_b32 s9, v254, 35
	s_nop 1
	v_cndmask_b32_e64 v5, v5, v193, s[8:9]
	v_readlane_b32 s8, v254, 36
	v_readlane_b32 s9, v254, 37
	s_nop 1
	v_cndmask_b32_e64 v5, v5, v214, s[8:9]
	v_readlane_b32 s8, v254, 38
	v_readlane_b32 s9, v254, 39
	s_nop 1
	v_cndmask_b32_e64 v5, v5, v126, s[8:9]
	v_readlane_b32 s8, v254, 40
	v_readlane_b32 s9, v254, 41
	s_nop 1
	v_cndmask_b32_e64 v5, v5, v127, s[8:9]
	v_readlane_b32 s8, v254, 42
	v_readlane_b32 s9, v254, 43
	s_nop 1
	v_cndmask_b32_e64 v5, v5, v94, s[8:9]
	v_readlane_b32 s8, v254, 44
	v_readlane_b32 s9, v254, 45
	s_nop 1
	v_cndmask_b32_e64 v5, v5, v16, s[8:9]
	v_readlane_b32 s8, v254, 46
	v_readlane_b32 s9, v254, 47
	s_nop 1
	v_cndmask_b32_e64 v5, v5, v12, s[8:9]
	v_readlane_b32 s8, v254, 48
	v_readlane_b32 s9, v254, 49
	s_nop 1
	v_cndmask_b32_e64 v0, v5, v0, s[8:9]
	v_add_f32_e32 v0, 0x358637bd, v0
	v_cmp_gt_f32_e32 vcc, s86, v0
	v_mul_f32_e32 v1, 0x4b800000, v0
	s_nop 0
	v_cndmask_b32_e32 v0, v0, v1, vcc
	v_rsq_f32_e32 v0, v0
	s_nop 0
	v_mul_f32_e32 v1, 0x45800000, v0
	v_cndmask_b32_e32 v0, v0, v1, vcc
	v_mul_f32_e32 v0, v170, v0
	ds_write_b32 v171, v0
